# static s_setprio 1 for waves 4-7 (the younger half) during the GEMM K-loops of P1 P5a P7 P8 P9, 0 outside
# speedup vs baseline: 1.0030x; 1.0006x over previous
.LBB0_199:
	s_ashr_i32 s17, s16, 31
	s_lshl_b64 s[18:19], s[16:17], 21
	s_add_u32 s18, s37, s18
	s_addc_u32 s19, s38, s19
	s_and_b64 s[20:21], s[4:5], exec
	s_cselect_b32 s17, s19, s7
	s_cselect_b32 s23, s18, s6
	s_ashr_i32 s15, s14, 31
	s_lshl_b64 s[20:21], s[14:15], 21
	s_add_u32 s20, s39, s20
	s_addc_u32 s21, s40, s21
	s_and_b64 s[28:29], s[4:5], exec
	s_cselect_b32 s15, s21, s27
	s_cselect_b32 s25, s20, s26
	s_add_u32 s6, s6, 0x100800
	s_addc_u32 s7, s7, 0
	s_add_u32 s30, s26, 0x1000
	v_mov_b32_e32 v0, 0
	s_addc_u32 s31, s27, 0
	s_mov_b32 s34, -2
	s_waitcnt lgkmcnt(0)
	v_mov_b32_e32 v1, v0
	v_mov_b32_e32 v2, v0
	v_mov_b32_e32 v3, v0
	v_mov_b32_e32 v4, v0
	v_mov_b32_e32 v5, v0
	v_mov_b32_e32 v6, v0
	v_mov_b32_e32 v7, v0
	v_mov_b32_e32 v8, v0
	v_mov_b32_e32 v9, v0
	v_mov_b32_e32 v10, v0
	v_mov_b32_e32 v11, v0
	v_mov_b32_e32 v12, v0
	v_mov_b32_e32 v13, v0
	v_mov_b32_e32 v14, v0
	v_mov_b32_e32 v15, v0
	v_mov_b32_e32 v16, v0
	v_mov_b32_e32 v17, v0
	v_mov_b32_e32 v18, v0
	v_mov_b32_e32 v19, v0
	v_mov_b32_e32 v20, v0
	v_mov_b32_e32 v21, v0
	v_mov_b32_e32 v22, v0
	v_mov_b32_e32 v23, v0
	v_mov_b32_e32 v24, v0
	v_mov_b32_e32 v25, v0
	v_mov_b32_e32 v26, v0
	v_mov_b32_e32 v27, v0
	v_mov_b32_e32 v28, v0
	v_mov_b32_e32 v29, v0
	v_mov_b32_e32 v30, v0
	v_mov_b32_e32 v31, v0
	v_mov_b32_e32 v64, v0
	v_mov_b32_e32 v65, v0
	v_mov_b32_e32 v66, v0
	v_mov_b32_e32 v67, v0
	v_mov_b32_e32 v68, v0
	v_mov_b32_e32 v69, v0
	v_mov_b32_e32 v70, v0
	v_mov_b32_e32 v71, v0
	v_mov_b32_e32 v72, v0
	v_mov_b32_e32 v73, v0
	v_mov_b32_e32 v74, v0
	v_mov_b32_e32 v75, v0
	v_mov_b32_e32 v76, v0
	v_mov_b32_e32 v77, v0
	v_mov_b32_e32 v78, v0
	v_mov_b32_e32 v79, v0
	v_mov_b32_e32 v80, v0
	v_mov_b32_e32 v81, v0
	v_mov_b32_e32 v82, v0
	v_mov_b32_e32 v83, v0
	v_mov_b32_e32 v84, v0
	v_mov_b32_e32 v85, v0
	v_mov_b32_e32 v86, v0
	v_mov_b32_e32 v87, v0
	v_mov_b32_e32 v88, v0
	v_mov_b32_e32 v89, v0
	v_mov_b32_e32 v90, v0
	v_mov_b32_e32 v91, v0
	v_mov_b32_e32 v92, v0
	v_mov_b32_e32 v93, v0
	v_mov_b32_e32 v94, v0
	v_mov_b32_e32 v95, v0
	v_mov_b32_e32 v32, v0
	v_mov_b32_e32 v33, v0
	v_mov_b32_e32 v34, v0
	v_mov_b32_e32 v35, v0
	v_mov_b32_e32 v36, v0
	v_mov_b32_e32 v37, v0
	v_mov_b32_e32 v38, v0
	v_mov_b32_e32 v39, v0
	v_mov_b32_e32 v40, v0
	v_mov_b32_e32 v41, v0
	v_mov_b32_e32 v42, v0
	v_mov_b32_e32 v43, v0
	v_mov_b32_e32 v44, v0
	v_mov_b32_e32 v45, v0
	v_mov_b32_e32 v46, v0
	v_mov_b32_e32 v47, v0
	v_mov_b32_e32 v48, v0
	v_mov_b32_e32 v49, v0
	v_mov_b32_e32 v50, v0
	v_mov_b32_e32 v51, v0
	v_mov_b32_e32 v52, v0
	v_mov_b32_e32 v53, v0
	v_mov_b32_e32 v54, v0
	v_mov_b32_e32 v55, v0
	v_mov_b32_e32 v56, v0
	v_mov_b32_e32 v57, v0
	v_mov_b32_e32 v58, v0
	v_mov_b32_e32 v59, v0
	v_mov_b32_e32 v60, v0
	v_mov_b32_e32 v61, v0
	v_mov_b32_e32 v62, v0
	v_mov_b32_e32 v63, v0
	v_mov_b32_e32 v96, v0
	v_mov_b32_e32 v97, v0
	v_mov_b32_e32 v98, v0
	v_mov_b32_e32 v99, v0
	v_mov_b32_e32 v100, v0
	v_mov_b32_e32 v101, v0
	v_mov_b32_e32 v102, v0
	v_mov_b32_e32 v103, v0
	v_mov_b32_e32 v104, v0
	v_mov_b32_e32 v105, v0
	v_mov_b32_e32 v106, v0
	v_mov_b32_e32 v107, v0
	v_mov_b32_e32 v108, v0
	v_mov_b32_e32 v109, v0
	v_mov_b32_e32 v110, v0
	v_mov_b32_e32 v111, v0
	v_mov_b32_e32 v112, v0
	v_mov_b32_e32 v113, v0
	v_mov_b32_e32 v114, v0
	v_mov_b32_e32 v115, v0
	v_mov_b32_e32 v116, v0
	v_mov_b32_e32 v117, v0
	v_mov_b32_e32 v118, v0
	v_mov_b32_e32 v119, v0
	v_mov_b32_e32 v120, v0
	v_mov_b32_e32 v121, v0
	v_mov_b32_e32 v122, v0
	v_mov_b32_e32 v123, v0
	v_mov_b32_e32 v124, v0
	v_mov_b32_e32 v125, v0
	v_mov_b32_e32 v126, v0
	v_mov_b32_e32 v127, v0
	s_and_b64 vcc, exec, s[0:1]
	s_cbranch_vccnz .Lsprio_P1
	s_setprio 1
.Lsprio_P1:
	.p2align 6
.LBB0_200:
	ds_read_b128 v[148:151], v169
	ds_read_b128 v[152:155], v169 offset:1024
	ds_read_b128 v[156:159], v169 offset:2048
	ds_read_b128 v[160:163], v169 offset:3072
	ds_read_b128 v[174:177], v170
	ds_read_b128 v[178:181], v170 offset:1024
	ds_read_b128 v[182:185], v170 offset:2048
	ds_read_b128 v[186:189], v170 offset:3072
	s_add_u32 s26, s6, 0xfff00800
	s_addc_u32 s27, s7, -1
	s_cmp_eq_u32 s34, 60
	s_cselect_b32 s29, s17, s27
	s_cselect_b32 s28, s23, s26
	s_cselect_b32 s27, s15, s31
	s_cselect_b32 s26, s25, s30
	v_lshl_add_u64 v[190:191], s[6:7], 0, v[138:139]
	s_add_i32 m0, s41, 0xc000
	s_nop 0
	global_load_lds_dwordx4 v[190:191], off
	v_lshl_add_u64 v[190:191], s[6:7], 0, v[140:141]
	s_add_i32 m0, s41, 0xe000
	s_nop 0
	global_load_lds_dwordx4 v[190:191], off
	ds_read_b128 v[190:193], v171
	ds_read_b128 v[194:197], v171 offset:1024
	ds_read_b128 v[198:201], v171 offset:2048
	ds_read_b128 v[202:205], v171 offset:3072
	ds_read_b128 v[206:209], v171 offset:4096
	ds_read_b128 v[210:213], v171 offset:5120
	ds_read_b128 v[214:217], v171 offset:6144
	ds_read_b128 v[218:221], v171 offset:7168
	s_waitcnt vmcnt(8)
	s_waitcnt lgkmcnt(0)
	s_barrier
	v_mfma_f32_16x16x32_bf16 v[124:127], v[148:151], v[190:193], v[124:127]
	v_mfma_f32_16x16x32_bf16 v[124:127], v[152:155], v[194:197], v[124:127]
	v_mfma_f32_16x16x32_bf16 v[120:123], v[160:163], v[194:197], v[120:123]
	v_mfma_f32_16x16x32_bf16 v[120:123], v[156:159], v[190:193], v[120:123]
	v_mfma_f32_16x16x32_bf16 v[60:63], v[174:177], v[190:193], v[60:63]
	v_mfma_f32_16x16x32_bf16 v[60:63], v[178:181], v[194:197], v[60:63]
	v_mfma_f32_16x16x32_bf16 v[56:59], v[186:189], v[194:197], v[56:59]
	v_mfma_f32_16x16x32_bf16 v[56:59], v[182:185], v[190:193], v[56:59]
	v_mfma_f32_16x16x32_bf16 v[48:51], v[182:185], v[198:201], v[48:51]
	v_mfma_f32_16x16x32_bf16 v[48:51], v[186:189], v[202:205], v[48:51]
	v_mfma_f32_16x16x32_bf16 v[52:55], v[178:181], v[202:205], v[52:55]
	v_mfma_f32_16x16x32_bf16 v[52:55], v[174:177], v[198:201], v[52:55]
	v_mfma_f32_16x16x32_bf16 v[112:115], v[156:159], v[198:201], v[112:115]
	v_mfma_f32_16x16x32_bf16 v[112:115], v[160:163], v[202:205], v[112:115]
	v_mfma_f32_16x16x32_bf16 v[116:119], v[152:155], v[202:205], v[116:119]
	v_mfma_f32_16x16x32_bf16 v[116:119], v[148:151], v[198:201], v[116:119]
	v_mfma_f32_16x16x32_bf16 v[108:111], v[148:151], v[206:209], v[108:111]
	v_mfma_f32_16x16x32_bf16 v[108:111], v[152:155], v[210:213], v[108:111]
	v_mfma_f32_16x16x32_bf16 v[104:107], v[160:163], v[210:213], v[104:107]
	v_mfma_f32_16x16x32_bf16 v[104:107], v[156:159], v[206:209], v[104:107]
	v_mfma_f32_16x16x32_bf16 v[44:47], v[174:177], v[206:209], v[44:47]
	v_mfma_f32_16x16x32_bf16 v[44:47], v[178:181], v[210:213], v[44:47]
	v_mfma_f32_16x16x32_bf16 v[40:43], v[186:189], v[210:213], v[40:43]
	v_mfma_f32_16x16x32_bf16 v[40:43], v[182:185], v[206:209], v[40:43]
	v_mfma_f32_16x16x32_bf16 v[32:35], v[182:185], v[214:217], v[32:35]
	v_mfma_f32_16x16x32_bf16 v[32:35], v[186:189], v[218:221], v[32:35]
	v_mfma_f32_16x16x32_bf16 v[36:39], v[178:181], v[218:221], v[36:39]
	v_mfma_f32_16x16x32_bf16 v[36:39], v[174:177], v[214:217], v[36:39]
	v_mfma_f32_16x16x32_bf16 v[96:99], v[156:159], v[214:217], v[96:99]
	v_mfma_f32_16x16x32_bf16 v[96:99], v[160:163], v[218:221], v[96:99]
	v_mfma_f32_16x16x32_bf16 v[100:103], v[152:155], v[218:221], v[100:103]
	v_mfma_f32_16x16x32_bf16 v[100:103], v[148:151], v[214:217], v[100:103]
	s_barrier
	s_add_i32 s35, s55, s36
	v_lshl_add_u64 v[222:223], s[26:27], 0, v[130:131]
	s_mov_b32 m0, s35
	v_lshl_add_u64 v[224:225], s[26:27], 0, v[134:135]
	global_load_lds_dwordx4 v[222:223], off
	s_add_i32 m0, s35, 0x2000
	s_add_u32 s58, s26, 0x100000
	s_addc_u32 s59, s27, 0
	s_add_i32 s35, s56, s36
	global_load_lds_dwordx4 v[224:225], off
	v_lshl_add_u64 v[190:191], s[58:59], 0, v[130:131]
	s_mov_b32 m0, s35
	v_lshl_add_u64 v[226:227], s[28:29], 0, v[128:129]
	global_load_lds_dwordx4 v[190:191], off
	v_lshl_add_u64 v[190:191], s[58:59], 0, v[134:135]
	s_add_i32 m0, s35, 0x2000
	v_lshl_add_u64 v[228:229], s[28:29], 0, v[132:133]
	global_load_lds_dwordx4 v[190:191], off
	s_mov_b32 m0, s41
	s_nop 0
	global_load_lds_dwordx4 v[226:227], off
	s_mov_b32 m0, s42
	s_nop 0
	global_load_lds_dwordx4 v[228:229], off
	ds_read_b128 v[190:193], v171 offset:16384
	ds_read_b128 v[194:197], v171 offset:17408
	ds_read_b128 v[198:201], v171 offset:18432
	ds_read_b128 v[202:205], v171 offset:19456
	ds_read_b128 v[206:209], v171 offset:20480
	ds_read_b128 v[210:213], v171 offset:21504
	ds_read_b128 v[214:217], v171 offset:22528
	ds_read_b128 v[218:221], v171 offset:23552
	s_waitcnt vmcnt(8)
	s_waitcnt lgkmcnt(0)
	s_barrier
	v_mfma_f32_16x16x32_bf16 v[92:95], v[148:151], v[190:193], v[92:95]
	v_mfma_f32_16x16x32_bf16 v[92:95], v[152:155], v[194:197], v[92:95]
	v_mfma_f32_16x16x32_bf16 v[88:91], v[160:163], v[194:197], v[88:91]
	v_mfma_f32_16x16x32_bf16 v[88:91], v[156:159], v[190:193], v[88:91]
	v_mfma_f32_16x16x32_bf16 v[28:31], v[174:177], v[190:193], v[28:31]
	v_mfma_f32_16x16x32_bf16 v[28:31], v[178:181], v[194:197], v[28:31]
	v_mfma_f32_16x16x32_bf16 v[24:27], v[186:189], v[194:197], v[24:27]
	v_mfma_f32_16x16x32_bf16 v[24:27], v[182:185], v[190:193], v[24:27]
	v_mfma_f32_16x16x32_bf16 v[16:19], v[182:185], v[198:201], v[16:19]
	v_mfma_f32_16x16x32_bf16 v[16:19], v[186:189], v[202:205], v[16:19]
	v_mfma_f32_16x16x32_bf16 v[20:23], v[178:181], v[202:205], v[20:23]
	v_mfma_f32_16x16x32_bf16 v[20:23], v[174:177], v[198:201], v[20:23]
	v_mfma_f32_16x16x32_bf16 v[80:83], v[156:159], v[198:201], v[80:83]
	v_mfma_f32_16x16x32_bf16 v[80:83], v[160:163], v[202:205], v[80:83]
	v_mfma_f32_16x16x32_bf16 v[84:87], v[152:155], v[202:205], v[84:87]
	v_mfma_f32_16x16x32_bf16 v[84:87], v[148:151], v[198:201], v[84:87]
	v_mfma_f32_16x16x32_bf16 v[76:79], v[148:151], v[206:209], v[76:79]
	v_mfma_f32_16x16x32_bf16 v[76:79], v[152:155], v[210:213], v[76:79]
	v_mfma_f32_16x16x32_bf16 v[72:75], v[160:163], v[210:213], v[72:75]
	v_mfma_f32_16x16x32_bf16 v[72:75], v[156:159], v[206:209], v[72:75]
	v_mfma_f32_16x16x32_bf16 v[12:15], v[174:177], v[206:209], v[12:15]
	v_mfma_f32_16x16x32_bf16 v[12:15], v[178:181], v[210:213], v[12:15]
	v_mfma_f32_16x16x32_bf16 v[8:11], v[186:189], v[210:213], v[8:11]
	v_mfma_f32_16x16x32_bf16 v[8:11], v[182:185], v[206:209], v[8:11]
	v_mfma_f32_16x16x32_bf16 v[0:3], v[182:185], v[214:217], v[0:3]
	v_mfma_f32_16x16x32_bf16 v[0:3], v[186:189], v[218:221], v[0:3]
	v_mfma_f32_16x16x32_bf16 v[4:7], v[178:181], v[218:221], v[4:7]
	v_mfma_f32_16x16x32_bf16 v[4:7], v[174:177], v[214:217], v[4:7]
	v_mfma_f32_16x16x32_bf16 v[64:67], v[156:159], v[214:217], v[64:67]
	v_mfma_f32_16x16x32_bf16 v[64:67], v[160:163], v[218:221], v[64:67]
	v_mfma_f32_16x16x32_bf16 v[68:71], v[152:155], v[218:221], v[68:71]
	v_mfma_f32_16x16x32_bf16 v[68:71], v[148:151], v[214:217], v[68:71]
	s_barrier
	s_add_i32 s35, 0, 0x18000
	v_add_u32_e32 v136, s35, v165
	s_add_i32 s57, 0, 0x1c000
	ds_read_b128 v[148:151], v136
	ds_read_b128 v[152:155], v136 offset:1024
	ds_read_b128 v[156:159], v136 offset:2048
	ds_read_b128 v[160:163], v136 offset:3072
	v_add_u32_e32 v136, s57, v165
	ds_read_b128 v[174:177], v136
	ds_read_b128 v[178:181], v136 offset:1024
	ds_read_b128 v[182:185], v136 offset:2048
	ds_read_b128 v[186:189], v136 offset:3072
	s_add_u32 s28, s28, 0x100000
	s_addc_u32 s29, s29, 0
	s_mov_b32 m0, s43
	v_lshl_add_u64 v[190:191], s[28:29], 0, v[128:129]
	global_load_lds_dwordx4 v[190:191], off
	v_lshl_add_u64 v[190:191], s[28:29], 0, v[132:133]
	s_mov_b32 m0, s44
	s_nop 0
	global_load_lds_dwordx4 v[190:191], off
	ds_read_b128 v[190:193], v171 offset:32768
	ds_read_b128 v[194:197], v171 offset:33792
	ds_read_b128 v[198:201], v171 offset:34816
	ds_read_b128 v[202:205], v171 offset:35840
	ds_read_b128 v[206:209], v171 offset:36864
	ds_read_b128 v[210:213], v171 offset:37888
	ds_read_b128 v[214:217], v171 offset:38912
	ds_read_b128 v[218:221], v171 offset:39936
	s_waitcnt vmcnt(8)
	s_waitcnt lgkmcnt(0)
	s_barrier
	v_mfma_f32_16x16x32_bf16 v[124:127], v[148:151], v[190:193], v[124:127]
	v_mfma_f32_16x16x32_bf16 v[124:127], v[152:155], v[194:197], v[124:127]
	v_mfma_f32_16x16x32_bf16 v[120:123], v[160:163], v[194:197], v[120:123]
	v_mfma_f32_16x16x32_bf16 v[120:123], v[156:159], v[190:193], v[120:123]
	v_mfma_f32_16x16x32_bf16 v[60:63], v[174:177], v[190:193], v[60:63]
	v_mfma_f32_16x16x32_bf16 v[60:63], v[178:181], v[194:197], v[60:63]
	v_mfma_f32_16x16x32_bf16 v[56:59], v[186:189], v[194:197], v[56:59]
	v_mfma_f32_16x16x32_bf16 v[56:59], v[182:185], v[190:193], v[56:59]
	v_mfma_f32_16x16x32_bf16 v[48:51], v[182:185], v[198:201], v[48:51]
	v_mfma_f32_16x16x32_bf16 v[48:51], v[186:189], v[202:205], v[48:51]
	v_mfma_f32_16x16x32_bf16 v[52:55], v[178:181], v[202:205], v[52:55]
	v_mfma_f32_16x16x32_bf16 v[52:55], v[174:177], v[198:201], v[52:55]
	v_mfma_f32_16x16x32_bf16 v[112:115], v[156:159], v[198:201], v[112:115]
	v_mfma_f32_16x16x32_bf16 v[112:115], v[160:163], v[202:205], v[112:115]
	v_mfma_f32_16x16x32_bf16 v[116:119], v[152:155], v[202:205], v[116:119]
	v_mfma_f32_16x16x32_bf16 v[116:119], v[148:151], v[198:201], v[116:119]
	v_mfma_f32_16x16x32_bf16 v[108:111], v[148:151], v[206:209], v[108:111]
	v_mfma_f32_16x16x32_bf16 v[108:111], v[152:155], v[210:213], v[108:111]
	v_mfma_f32_16x16x32_bf16 v[104:107], v[160:163], v[210:213], v[104:107]
	v_mfma_f32_16x16x32_bf16 v[104:107], v[156:159], v[206:209], v[104:107]
	v_mfma_f32_16x16x32_bf16 v[44:47], v[174:177], v[206:209], v[44:47]
	v_mfma_f32_16x16x32_bf16 v[44:47], v[178:181], v[210:213], v[44:47]
	v_mfma_f32_16x16x32_bf16 v[40:43], v[186:189], v[210:213], v[40:43]
	v_mfma_f32_16x16x32_bf16 v[40:43], v[182:185], v[206:209], v[40:43]
	v_mfma_f32_16x16x32_bf16 v[32:35], v[182:185], v[214:217], v[32:35]
	v_mfma_f32_16x16x32_bf16 v[32:35], v[186:189], v[218:221], v[32:35]
	v_mfma_f32_16x16x32_bf16 v[36:39], v[178:181], v[218:221], v[36:39]
	v_mfma_f32_16x16x32_bf16 v[36:39], v[174:177], v[214:217], v[36:39]
	v_mfma_f32_16x16x32_bf16 v[96:99], v[156:159], v[214:217], v[96:99]
	v_mfma_f32_16x16x32_bf16 v[96:99], v[160:163], v[218:221], v[96:99]
	v_mfma_f32_16x16x32_bf16 v[100:103], v[152:155], v[218:221], v[100:103]
	v_mfma_f32_16x16x32_bf16 v[100:103], v[148:151], v[214:217], v[100:103]
	s_barrier
	s_add_i32 s28, s35, s36
	v_lshl_add_u64 v[190:191], v[222:223], 0, s[12:13]
	s_mov_b32 m0, s28
	s_nop 0
	global_load_lds_dwordx4 v[190:191], off
	s_add_i32 m0, s28, 0x2000
	s_add_u32 s26, s26, 0x100800
	v_lshl_add_u64 v[190:191], v[224:225], 0, s[12:13]
	s_addc_u32 s27, s27, 0
	s_add_i32 s28, s57, s36
	global_load_lds_dwordx4 v[190:191], off
	v_lshl_add_u64 v[190:191], s[26:27], 0, v[130:131]
	s_mov_b32 m0, s28
	s_nop 0
	global_load_lds_dwordx4 v[190:191], off
	v_lshl_add_u64 v[190:191], s[26:27], 0, v[134:135]
	s_add_i32 m0, s28, 0x2000
	s_nop 0
	global_load_lds_dwordx4 v[190:191], off
	v_lshl_add_u64 v[190:191], v[226:227], 0, s[12:13]
	s_mov_b32 m0, s49
	s_nop 0
	global_load_lds_dwordx4 v[190:191], off
	v_lshl_add_u64 v[190:191], v[228:229], 0, s[12:13]
	s_mov_b32 m0, s50
	s_nop 0
	global_load_lds_dwordx4 v[190:191], off
	ds_read_b128 v[190:193], v171 offset:49152
	ds_read_b128 v[194:197], v171 offset:50176
	ds_read_b128 v[198:201], v171 offset:51200
	ds_read_b128 v[202:205], v171 offset:52224
	ds_read_b128 v[206:209], v171 offset:53248
	ds_read_b128 v[210:213], v171 offset:54272
	ds_read_b128 v[214:217], v171 offset:55296
	ds_read_b128 v[218:221], v171 offset:56320
	s_waitcnt vmcnt(8)
	s_waitcnt lgkmcnt(0)
	s_barrier
	v_mfma_f32_16x16x32_bf16 v[92:95], v[148:151], v[190:193], v[92:95]
	v_mfma_f32_16x16x32_bf16 v[92:95], v[152:155], v[194:197], v[92:95]
	v_mfma_f32_16x16x32_bf16 v[88:91], v[160:163], v[194:197], v[88:91]
	v_mfma_f32_16x16x32_bf16 v[88:91], v[156:159], v[190:193], v[88:91]
	v_mfma_f32_16x16x32_bf16 v[28:31], v[174:177], v[190:193], v[28:31]
	v_mfma_f32_16x16x32_bf16 v[28:31], v[178:181], v[194:197], v[28:31]
	v_mfma_f32_16x16x32_bf16 v[24:27], v[186:189], v[194:197], v[24:27]
	v_mfma_f32_16x16x32_bf16 v[24:27], v[182:185], v[190:193], v[24:27]
	v_mfma_f32_16x16x32_bf16 v[16:19], v[182:185], v[198:201], v[16:19]
	v_mfma_f32_16x16x32_bf16 v[16:19], v[186:189], v[202:205], v[16:19]
	v_mfma_f32_16x16x32_bf16 v[20:23], v[178:181], v[202:205], v[20:23]
	v_mfma_f32_16x16x32_bf16 v[20:23], v[174:177], v[198:201], v[20:23]
	v_mfma_f32_16x16x32_bf16 v[80:83], v[156:159], v[198:201], v[80:83]
	v_mfma_f32_16x16x32_bf16 v[80:83], v[160:163], v[202:205], v[80:83]
	v_mfma_f32_16x16x32_bf16 v[84:87], v[152:155], v[202:205], v[84:87]
	v_mfma_f32_16x16x32_bf16 v[84:87], v[148:151], v[198:201], v[84:87]
	v_mfma_f32_16x16x32_bf16 v[76:79], v[148:151], v[206:209], v[76:79]
	v_mfma_f32_16x16x32_bf16 v[76:79], v[152:155], v[210:213], v[76:79]
	v_mfma_f32_16x16x32_bf16 v[72:75], v[160:163], v[210:213], v[72:75]
	v_mfma_f32_16x16x32_bf16 v[72:75], v[156:159], v[206:209], v[72:75]
	v_mfma_f32_16x16x32_bf16 v[12:15], v[174:177], v[206:209], v[12:15]
	v_mfma_f32_16x16x32_bf16 v[12:15], v[178:181], v[210:213], v[12:15]
	v_mfma_f32_16x16x32_bf16 v[8:11], v[186:189], v[210:213], v[8:11]
	v_mfma_f32_16x16x32_bf16 v[8:11], v[182:185], v[206:209], v[8:11]
	v_mfma_f32_16x16x32_bf16 v[0:3], v[182:185], v[214:217], v[0:3]
	v_mfma_f32_16x16x32_bf16 v[0:3], v[186:189], v[218:221], v[0:3]
	v_mfma_f32_16x16x32_bf16 v[4:7], v[178:181], v[218:221], v[4:7]
	v_mfma_f32_16x16x32_bf16 v[4:7], v[174:177], v[214:217], v[4:7]
	v_mfma_f32_16x16x32_bf16 v[64:67], v[156:159], v[214:217], v[64:67]
	v_mfma_f32_16x16x32_bf16 v[64:67], v[160:163], v[218:221], v[64:67]
	v_mfma_f32_16x16x32_bf16 v[68:71], v[152:155], v[218:221], v[68:71]
	v_mfma_f32_16x16x32_bf16 v[68:71], v[148:151], v[214:217], v[68:71]
	s_barrier
	s_add_i32 s34, s34, 2
	s_add_u32 s6, s6, 0x1000
	s_addc_u32 s7, s7, 0
	s_add_u32 s30, s30, 0x1000
	s_addc_u32 s31, s31, 0
	s_cmp_gt_u32 s34, 61
	s_cbranch_scc0 .LBB0_200
	s_setprio 0

.LBB0_1201:
	s_ashr_i32 s23, s22, 31
	s_lshl_b64 s[24:25], s[22:23], 21
	s_add_u32 s24, s55, s24
	s_addc_u32 s25, s56, s25
	s_and_b64 s[26:27], s[4:5], exec
	s_cselect_b32 s23, s25, s31
	s_cselect_b32 s36, s24, s30
	s_ashr_i32 s21, s20, 31
	s_lshl_b64 s[26:27], s[20:21], 21
	s_add_u32 s26, s57, s26
	s_addc_u32 s27, s58, s27
	s_and_b64 s[34:35], s[4:5], exec
	s_cselect_b32 s21, s27, s29
	s_cselect_b32 s37, s26, s28
	s_add_u32 s38, s28, 0x1000
	s_addc_u32 s39, s29, 0
	s_add_u32 s28, s30, 0x100080
	v_mov_b32_e32 v0, 0
	s_addc_u32 s29, s31, 0
	s_mov_b32 s40, -2
	s_waitcnt lgkmcnt(0)
	v_mov_b32_e32 v1, v0
	v_mov_b32_e32 v2, v0
	v_mov_b32_e32 v3, v0
	v_mov_b32_e32 v4, v0
	v_mov_b32_e32 v5, v0
	v_mov_b32_e32 v6, v0
	v_mov_b32_e32 v7, v0
	v_mov_b32_e32 v16, v0
	v_mov_b32_e32 v17, v0
	v_mov_b32_e32 v18, v0
	v_mov_b32_e32 v19, v0
	v_mov_b32_e32 v20, v0
	v_mov_b32_e32 v21, v0
	v_mov_b32_e32 v22, v0
	v_mov_b32_e32 v23, v0
	v_mov_b32_e32 v32, v0
	v_mov_b32_e32 v33, v0
	v_mov_b32_e32 v34, v0
	v_mov_b32_e32 v35, v0
	v_mov_b32_e32 v36, v0
	v_mov_b32_e32 v37, v0
	v_mov_b32_e32 v38, v0
	v_mov_b32_e32 v39, v0
	v_mov_b32_e32 v48, v0
	v_mov_b32_e32 v49, v0
	v_mov_b32_e32 v50, v0
	v_mov_b32_e32 v51, v0
	v_mov_b32_e32 v52, v0
	v_mov_b32_e32 v53, v0
	v_mov_b32_e32 v54, v0
	v_mov_b32_e32 v55, v0
	v_mov_b32_e32 v8, v0
	v_mov_b32_e32 v9, v0
	v_mov_b32_e32 v10, v0
	v_mov_b32_e32 v11, v0
	v_mov_b32_e32 v12, v0
	v_mov_b32_e32 v13, v0
	v_mov_b32_e32 v14, v0
	v_mov_b32_e32 v15, v0
	v_mov_b32_e32 v24, v0
	v_mov_b32_e32 v25, v0
	v_mov_b32_e32 v26, v0
	v_mov_b32_e32 v27, v0
	v_mov_b32_e32 v28, v0
	v_mov_b32_e32 v29, v0
	v_mov_b32_e32 v30, v0
	v_mov_b32_e32 v31, v0
	v_mov_b32_e32 v40, v0
	v_mov_b32_e32 v41, v0
	v_mov_b32_e32 v42, v0
	v_mov_b32_e32 v43, v0
	v_mov_b32_e32 v44, v0
	v_mov_b32_e32 v45, v0
	v_mov_b32_e32 v46, v0
	v_mov_b32_e32 v47, v0
	v_mov_b32_e32 v56, v0
	v_mov_b32_e32 v57, v0
	v_mov_b32_e32 v58, v0
	v_mov_b32_e32 v59, v0
	v_mov_b32_e32 v60, v0
	v_mov_b32_e32 v61, v0
	v_mov_b32_e32 v62, v0
	v_mov_b32_e32 v63, v0
	v_mov_b32_e32 v64, v0
	v_mov_b32_e32 v65, v0
	v_mov_b32_e32 v66, v0
	v_mov_b32_e32 v67, v0
	v_mov_b32_e32 v68, v0
	v_mov_b32_e32 v69, v0
	v_mov_b32_e32 v70, v0
	v_mov_b32_e32 v71, v0
	v_mov_b32_e32 v80, v0
	v_mov_b32_e32 v81, v0
	v_mov_b32_e32 v82, v0
	v_mov_b32_e32 v83, v0
	v_mov_b32_e32 v84, v0
	v_mov_b32_e32 v85, v0
	v_mov_b32_e32 v86, v0
	v_mov_b32_e32 v87, v0
	v_mov_b32_e32 v96, v0
	v_mov_b32_e32 v97, v0
	v_mov_b32_e32 v98, v0
	v_mov_b32_e32 v99, v0
	v_mov_b32_e32 v100, v0
	v_mov_b32_e32 v101, v0
	v_mov_b32_e32 v102, v0
	v_mov_b32_e32 v103, v0
	v_mov_b32_e32 v112, v0
	v_mov_b32_e32 v113, v0
	v_mov_b32_e32 v114, v0
	v_mov_b32_e32 v115, v0
	v_mov_b32_e32 v116, v0
	v_mov_b32_e32 v117, v0
	v_mov_b32_e32 v118, v0
	v_mov_b32_e32 v119, v0
	v_mov_b32_e32 v72, v0
	v_mov_b32_e32 v73, v0
	v_mov_b32_e32 v74, v0
	v_mov_b32_e32 v75, v0
	v_mov_b32_e32 v76, v0
	v_mov_b32_e32 v77, v0
	v_mov_b32_e32 v78, v0
	v_mov_b32_e32 v79, v0
	v_mov_b32_e32 v88, v0
	v_mov_b32_e32 v89, v0
	v_mov_b32_e32 v90, v0
	v_mov_b32_e32 v91, v0
	v_mov_b32_e32 v92, v0
	v_mov_b32_e32 v93, v0
	v_mov_b32_e32 v94, v0
	v_mov_b32_e32 v95, v0
	v_mov_b32_e32 v104, v0
	v_mov_b32_e32 v105, v0
	v_mov_b32_e32 v106, v0
	v_mov_b32_e32 v107, v0
	v_mov_b32_e32 v108, v0
	v_mov_b32_e32 v109, v0
	v_mov_b32_e32 v110, v0
	v_mov_b32_e32 v111, v0
	v_mov_b32_e32 v120, v0
	v_mov_b32_e32 v121, v0
	v_mov_b32_e32 v122, v0
	v_mov_b32_e32 v123, v0
	v_mov_b32_e32 v124, v0
	v_mov_b32_e32 v125, v0
	v_mov_b32_e32 v126, v0
	v_mov_b32_e32 v127, v0
	s_and_b64 vcc, exec, s[10:11]
	s_cbranch_vccnz .Lsprio_P5a
	s_setprio 1

.LBB0_1202:
	ds_read_b128 v[128:131], v176
	ds_read_b128 v[132:135], v176 offset:1024
	ds_read_b128 v[136:139], v176 offset:2048
	ds_read_b128 v[140:143], v176 offset:3072
	ds_read_b128 v[144:147], v177
	ds_read_b128 v[148:151], v177 offset:1024
	ds_read_b128 v[180:183], v177 offset:2048
	ds_read_b128 v[184:187], v177 offset:3072
	s_add_u32 s30, s28, 0xfff00080
	s_addc_u32 s31, s29, -1
	s_cmp_eq_u32 s40, 60
	s_cselect_b32 s35, s23, s31
	s_cselect_b32 s34, s36, s30
	s_cselect_b32 s31, s21, s39
	s_cselect_b32 s30, s37, s38
	v_lshl_add_u64 v[172:173], s[28:29], 0, v[164:165]
	s_add_i32 m0, s7, 0xc000
	s_nop 0
	global_load_lds_dwordx4 v[172:173], off
	v_lshl_add_u64 v[172:173], s[28:29], 0, v[166:167]
	s_add_i32 m0, s7, 0xe000
	s_nop 0
	global_load_lds_dwordx4 v[172:173], off
	ds_read_b128 v[188:191], v178
	ds_read_b128 v[192:195], v178 offset:1024
	ds_read_b128 v[196:199], v178 offset:2048
	ds_read_b128 v[200:203], v178 offset:3072
	ds_read_b128 v[204:207], v178 offset:4096
	ds_read_b128 v[208:211], v178 offset:5120
	ds_read_b128 v[212:215], v178 offset:6144
	ds_read_b128 v[216:219], v178 offset:7168
	s_waitcnt vmcnt(8)
	s_waitcnt lgkmcnt(0)
	s_barrier
	v_mfma_f32_16x16x32_bf16 v[124:127], v[128:131], v[188:191], v[124:127]
	v_mfma_f32_16x16x32_bf16 v[124:127], v[132:135], v[192:195], v[124:127]
	v_mfma_f32_16x16x32_bf16 v[120:123], v[140:143], v[192:195], v[120:123]
	v_mfma_f32_16x16x32_bf16 v[120:123], v[136:139], v[188:191], v[120:123]
	v_mfma_f32_16x16x32_bf16 v[116:119], v[144:147], v[188:191], v[116:119]
	v_mfma_f32_16x16x32_bf16 v[116:119], v[148:151], v[192:195], v[116:119]
	v_mfma_f32_16x16x32_bf16 v[112:115], v[184:187], v[192:195], v[112:115]
	v_mfma_f32_16x16x32_bf16 v[112:115], v[180:183], v[188:191], v[112:115]
	v_mfma_f32_16x16x32_bf16 v[96:99], v[180:183], v[196:199], v[96:99]
	v_mfma_f32_16x16x32_bf16 v[96:99], v[184:187], v[200:203], v[96:99]
	v_mfma_f32_16x16x32_bf16 v[100:103], v[148:151], v[200:203], v[100:103]
	v_mfma_f32_16x16x32_bf16 v[100:103], v[144:147], v[196:199], v[100:103]
	v_mfma_f32_16x16x32_bf16 v[104:107], v[136:139], v[196:199], v[104:107]
	v_mfma_f32_16x16x32_bf16 v[104:107], v[140:143], v[200:203], v[104:107]
	v_mfma_f32_16x16x32_bf16 v[108:111], v[132:135], v[200:203], v[108:111]
	v_mfma_f32_16x16x32_bf16 v[108:111], v[128:131], v[196:199], v[108:111]
	v_mfma_f32_16x16x32_bf16 v[92:95], v[128:131], v[204:207], v[92:95]
	v_mfma_f32_16x16x32_bf16 v[92:95], v[132:135], v[208:211], v[92:95]
	v_mfma_f32_16x16x32_bf16 v[88:91], v[140:143], v[208:211], v[88:91]
	v_mfma_f32_16x16x32_bf16 v[88:91], v[136:139], v[204:207], v[88:91]
	v_mfma_f32_16x16x32_bf16 v[84:87], v[144:147], v[204:207], v[84:87]
	v_mfma_f32_16x16x32_bf16 v[84:87], v[148:151], v[208:211], v[84:87]
	v_mfma_f32_16x16x32_bf16 v[80:83], v[184:187], v[208:211], v[80:83]
	v_mfma_f32_16x16x32_bf16 v[80:83], v[180:183], v[204:207], v[80:83]
	v_mfma_f32_16x16x32_bf16 v[64:67], v[180:183], v[212:215], v[64:67]
	v_mfma_f32_16x16x32_bf16 v[64:67], v[184:187], v[216:219], v[64:67]
	v_mfma_f32_16x16x32_bf16 v[68:71], v[148:151], v[216:219], v[68:71]
	v_mfma_f32_16x16x32_bf16 v[68:71], v[144:147], v[212:215], v[68:71]
	v_mfma_f32_16x16x32_bf16 v[72:75], v[136:139], v[212:215], v[72:75]
	v_mfma_f32_16x16x32_bf16 v[72:75], v[140:143], v[216:219], v[72:75]
	v_mfma_f32_16x16x32_bf16 v[76:79], v[132:135], v[216:219], v[76:79]
	v_mfma_f32_16x16x32_bf16 v[76:79], v[128:131], v[212:215], v[76:79]
	s_barrier
	s_add_i32 s41, s68, s33
	v_lshl_add_u64 v[172:173], s[30:31], 0, v[154:155]
	s_mov_b32 m0, s41
	v_lshl_add_u64 v[220:221], s[30:31], 0, v[158:159]
	global_load_lds_dwordx4 v[172:173], off
	s_add_i32 m0, s41, 0x2000
	s_add_u32 s42, s30, 0x100000
	s_addc_u32 s43, s31, 0
	s_add_i32 s41, s69, s33
	global_load_lds_dwordx4 v[220:221], off
	v_lshl_add_u64 v[188:189], s[42:43], 0, v[154:155]
	s_mov_b32 m0, s41
	v_lshl_add_u64 v[222:223], s[34:35], 0, v[152:153]
	global_load_lds_dwordx4 v[188:189], off
	v_lshl_add_u64 v[188:189], s[42:43], 0, v[158:159]
	s_add_i32 m0, s41, 0x2000
	v_lshl_add_u64 v[224:225], s[34:35], 0, v[156:157]
	global_load_lds_dwordx4 v[188:189], off
	s_mov_b32 m0, s7
	s_nop 0
	global_load_lds_dwordx4 v[222:223], off
	s_mov_b32 m0, s59
	s_nop 0
	global_load_lds_dwordx4 v[224:225], off
	ds_read_b128 v[188:191], v178 offset:16384
	ds_read_b128 v[192:195], v178 offset:17408
	ds_read_b128 v[196:199], v178 offset:18432
	ds_read_b128 v[200:203], v178 offset:19456
	ds_read_b128 v[204:207], v178 offset:20480
	ds_read_b128 v[208:211], v178 offset:21504
	ds_read_b128 v[212:215], v178 offset:22528
	ds_read_b128 v[216:219], v178 offset:23552
	s_waitcnt vmcnt(8)
	s_waitcnt lgkmcnt(0)
	s_barrier
	v_mfma_f32_16x16x32_bf16 v[60:63], v[128:131], v[188:191], v[60:63]
	v_mfma_f32_16x16x32_bf16 v[60:63], v[132:135], v[192:195], v[60:63]
	v_mfma_f32_16x16x32_bf16 v[56:59], v[140:143], v[192:195], v[56:59]
	v_mfma_f32_16x16x32_bf16 v[56:59], v[136:139], v[188:191], v[56:59]
	v_mfma_f32_16x16x32_bf16 v[52:55], v[144:147], v[188:191], v[52:55]
	v_mfma_f32_16x16x32_bf16 v[52:55], v[148:151], v[192:195], v[52:55]
	v_mfma_f32_16x16x32_bf16 v[48:51], v[184:187], v[192:195], v[48:51]
	v_mfma_f32_16x16x32_bf16 v[48:51], v[180:183], v[188:191], v[48:51]
	v_mfma_f32_16x16x32_bf16 v[32:35], v[180:183], v[196:199], v[32:35]
	v_mfma_f32_16x16x32_bf16 v[32:35], v[184:187], v[200:203], v[32:35]
	v_mfma_f32_16x16x32_bf16 v[36:39], v[148:151], v[200:203], v[36:39]
	v_mfma_f32_16x16x32_bf16 v[36:39], v[144:147], v[196:199], v[36:39]
	v_mfma_f32_16x16x32_bf16 v[40:43], v[136:139], v[196:199], v[40:43]
	v_mfma_f32_16x16x32_bf16 v[40:43], v[140:143], v[200:203], v[40:43]
	v_mfma_f32_16x16x32_bf16 v[44:47], v[132:135], v[200:203], v[44:47]
	v_mfma_f32_16x16x32_bf16 v[44:47], v[128:131], v[196:199], v[44:47]
	v_mfma_f32_16x16x32_bf16 v[28:31], v[128:131], v[204:207], v[28:31]
	v_mfma_f32_16x16x32_bf16 v[28:31], v[132:135], v[208:211], v[28:31]
	v_mfma_f32_16x16x32_bf16 v[24:27], v[140:143], v[208:211], v[24:27]
	v_mfma_f32_16x16x32_bf16 v[24:27], v[136:139], v[204:207], v[24:27]
	v_mfma_f32_16x16x32_bf16 v[20:23], v[144:147], v[204:207], v[20:23]
	v_mfma_f32_16x16x32_bf16 v[20:23], v[148:151], v[208:211], v[20:23]
	v_mfma_f32_16x16x32_bf16 v[16:19], v[184:187], v[208:211], v[16:19]
	v_mfma_f32_16x16x32_bf16 v[16:19], v[180:183], v[204:207], v[16:19]
	v_mfma_f32_16x16x32_bf16 v[0:3], v[180:183], v[212:215], v[0:3]
	v_mfma_f32_16x16x32_bf16 v[0:3], v[184:187], v[216:219], v[0:3]
	v_mfma_f32_16x16x32_bf16 v[4:7], v[148:151], v[216:219], v[4:7]
	v_mfma_f32_16x16x32_bf16 v[4:7], v[144:147], v[212:215], v[4:7]
	v_mfma_f32_16x16x32_bf16 v[8:11], v[136:139], v[212:215], v[8:11]
	v_mfma_f32_16x16x32_bf16 v[8:11], v[140:143], v[216:219], v[8:11]
	v_mfma_f32_16x16x32_bf16 v[12:15], v[132:135], v[216:219], v[12:15]
	v_mfma_f32_16x16x32_bf16 v[12:15], v[128:131], v[212:215], v[12:15]
	s_barrier
	s_add_i32 s41, 0, 0x18000
	s_add_i32 s42, 0, 0x1c000
	v_add_u32_e32 v140, s41, v174
	v_add_u32_e32 v184, s42, v174
	ds_read_b128 v[128:131], v140
	ds_read_b128 v[132:135], v140 offset:1024
	ds_read_b128 v[136:139], v140 offset:2048
	ds_read_b128 v[140:143], v140 offset:3072
	ds_read_b128 v[144:147], v184
	ds_read_b128 v[148:151], v184 offset:1024
	ds_read_b128 v[180:183], v184 offset:2048
	ds_read_b128 v[184:187], v184 offset:3072
	s_add_u32 s34, s34, 0x100000
	s_addc_u32 s35, s35, 0
	s_mov_b32 m0, s60
	v_lshl_add_u64 v[188:189], s[34:35], 0, v[152:153]
	global_load_lds_dwordx4 v[188:189], off
	v_lshl_add_u64 v[188:189], s[34:35], 0, v[156:157]
	s_mov_b32 m0, s61
	s_nop 0
	global_load_lds_dwordx4 v[188:189], off
	ds_read_b128 v[188:191], v178 offset:32768
	ds_read_b128 v[192:195], v178 offset:33792
	ds_read_b128 v[196:199], v178 offset:34816
	ds_read_b128 v[200:203], v178 offset:35840
	ds_read_b128 v[204:207], v178 offset:36864
	ds_read_b128 v[208:211], v178 offset:37888
	ds_read_b128 v[212:215], v178 offset:38912
	ds_read_b128 v[216:219], v178 offset:39936
	s_waitcnt vmcnt(8)
	s_waitcnt lgkmcnt(0)
	s_barrier
	v_mfma_f32_16x16x32_bf16 v[124:127], v[128:131], v[188:191], v[124:127]
	v_mfma_f32_16x16x32_bf16 v[124:127], v[132:135], v[192:195], v[124:127]
	v_mfma_f32_16x16x32_bf16 v[120:123], v[140:143], v[192:195], v[120:123]
	v_mfma_f32_16x16x32_bf16 v[120:123], v[136:139], v[188:191], v[120:123]
	v_mfma_f32_16x16x32_bf16 v[116:119], v[144:147], v[188:191], v[116:119]
	v_mfma_f32_16x16x32_bf16 v[116:119], v[148:151], v[192:195], v[116:119]
	v_mfma_f32_16x16x32_bf16 v[112:115], v[184:187], v[192:195], v[112:115]
	v_mfma_f32_16x16x32_bf16 v[112:115], v[180:183], v[188:191], v[112:115]
	v_mfma_f32_16x16x32_bf16 v[96:99], v[180:183], v[196:199], v[96:99]
	v_mfma_f32_16x16x32_bf16 v[96:99], v[184:187], v[200:203], v[96:99]
	v_mfma_f32_16x16x32_bf16 v[100:103], v[148:151], v[200:203], v[100:103]
	v_mfma_f32_16x16x32_bf16 v[100:103], v[144:147], v[196:199], v[100:103]
	v_mfma_f32_16x16x32_bf16 v[104:107], v[136:139], v[196:199], v[104:107]
	v_mfma_f32_16x16x32_bf16 v[104:107], v[140:143], v[200:203], v[104:107]
	v_mfma_f32_16x16x32_bf16 v[108:111], v[132:135], v[200:203], v[108:111]
	v_mfma_f32_16x16x32_bf16 v[108:111], v[128:131], v[196:199], v[108:111]
	v_mfma_f32_16x16x32_bf16 v[92:95], v[128:131], v[204:207], v[92:95]
	v_mfma_f32_16x16x32_bf16 v[92:95], v[132:135], v[208:211], v[92:95]
	v_mfma_f32_16x16x32_bf16 v[88:91], v[140:143], v[208:211], v[88:91]
	v_mfma_f32_16x16x32_bf16 v[88:91], v[136:139], v[204:207], v[88:91]
	v_mfma_f32_16x16x32_bf16 v[84:87], v[144:147], v[204:207], v[84:87]
	v_mfma_f32_16x16x32_bf16 v[84:87], v[148:151], v[208:211], v[84:87]
	v_mfma_f32_16x16x32_bf16 v[80:83], v[184:187], v[208:211], v[80:83]
	v_mfma_f32_16x16x32_bf16 v[80:83], v[180:183], v[204:207], v[80:83]
	v_mfma_f32_16x16x32_bf16 v[64:67], v[180:183], v[212:215], v[64:67]
	v_mfma_f32_16x16x32_bf16 v[64:67], v[184:187], v[216:219], v[64:67]
	v_mfma_f32_16x16x32_bf16 v[68:71], v[148:151], v[216:219], v[68:71]
	v_mfma_f32_16x16x32_bf16 v[68:71], v[144:147], v[212:215], v[68:71]
	v_mfma_f32_16x16x32_bf16 v[72:75], v[136:139], v[212:215], v[72:75]
	v_mfma_f32_16x16x32_bf16 v[72:75], v[140:143], v[216:219], v[72:75]
	v_mfma_f32_16x16x32_bf16 v[76:79], v[132:135], v[216:219], v[76:79]
	v_mfma_f32_16x16x32_bf16 v[76:79], v[128:131], v[212:215], v[76:79]
	s_barrier
	s_add_i32 s34, s41, s33
	v_lshl_add_u64 v[172:173], v[172:173], 0, s[16:17]
	s_mov_b32 m0, s34
	s_nop 0
	global_load_lds_dwordx4 v[172:173], off
	s_add_i32 m0, s34, 0x2000
	s_add_u32 s30, s30, 0x100800
	v_lshl_add_u64 v[172:173], v[220:221], 0, s[16:17]
	s_addc_u32 s31, s31, 0
	s_add_i32 s34, s42, s33
	global_load_lds_dwordx4 v[172:173], off
	v_lshl_add_u64 v[172:173], s[30:31], 0, v[154:155]
	s_mov_b32 m0, s34
	s_nop 0
	global_load_lds_dwordx4 v[172:173], off
	v_lshl_add_u64 v[172:173], s[30:31], 0, v[158:159]
	s_add_i32 m0, s34, 0x2000
	s_nop 0
	global_load_lds_dwordx4 v[172:173], off
	v_lshl_add_u64 v[172:173], v[222:223], 0, s[18:19]
	s_mov_b32 m0, s63
	s_nop 0
	global_load_lds_dwordx4 v[172:173], off
	v_lshl_add_u64 v[172:173], v[224:225], 0, s[18:19]
	s_mov_b32 m0, s64
	s_nop 0
	global_load_lds_dwordx4 v[172:173], off
	ds_read_b128 v[188:191], v178 offset:49152
	ds_read_b128 v[192:195], v178 offset:50176
	ds_read_b128 v[196:199], v178 offset:51200
	ds_read_b128 v[200:203], v178 offset:52224
	ds_read_b128 v[204:207], v178 offset:53248
	ds_read_b128 v[208:211], v178 offset:54272
	ds_read_b128 v[212:215], v178 offset:55296
	ds_read_b128 v[216:219], v178 offset:56320
	s_waitcnt vmcnt(8)
	s_waitcnt lgkmcnt(0)
	s_barrier
	v_mfma_f32_16x16x32_bf16 v[60:63], v[128:131], v[188:191], v[60:63]
	v_mfma_f32_16x16x32_bf16 v[60:63], v[132:135], v[192:195], v[60:63]
	v_mfma_f32_16x16x32_bf16 v[56:59], v[140:143], v[192:195], v[56:59]
	v_mfma_f32_16x16x32_bf16 v[56:59], v[136:139], v[188:191], v[56:59]
	v_mfma_f32_16x16x32_bf16 v[52:55], v[144:147], v[188:191], v[52:55]
	v_mfma_f32_16x16x32_bf16 v[52:55], v[148:151], v[192:195], v[52:55]
	v_mfma_f32_16x16x32_bf16 v[48:51], v[184:187], v[192:195], v[48:51]
	v_mfma_f32_16x16x32_bf16 v[48:51], v[180:183], v[188:191], v[48:51]
	v_mfma_f32_16x16x32_bf16 v[32:35], v[180:183], v[196:199], v[32:35]
	v_mfma_f32_16x16x32_bf16 v[32:35], v[184:187], v[200:203], v[32:35]
	v_mfma_f32_16x16x32_bf16 v[36:39], v[148:151], v[200:203], v[36:39]
	v_mfma_f32_16x16x32_bf16 v[36:39], v[144:147], v[196:199], v[36:39]
	v_mfma_f32_16x16x32_bf16 v[40:43], v[136:139], v[196:199], v[40:43]
	v_mfma_f32_16x16x32_bf16 v[40:43], v[140:143], v[200:203], v[40:43]
	v_mfma_f32_16x16x32_bf16 v[44:47], v[132:135], v[200:203], v[44:47]
	v_mfma_f32_16x16x32_bf16 v[44:47], v[128:131], v[196:199], v[44:47]
	v_mfma_f32_16x16x32_bf16 v[28:31], v[128:131], v[204:207], v[28:31]
	v_mfma_f32_16x16x32_bf16 v[28:31], v[132:135], v[208:211], v[28:31]
	v_mfma_f32_16x16x32_bf16 v[24:27], v[140:143], v[208:211], v[24:27]
	v_mfma_f32_16x16x32_bf16 v[24:27], v[136:139], v[204:207], v[24:27]
	v_mfma_f32_16x16x32_bf16 v[20:23], v[144:147], v[204:207], v[20:23]
	v_mfma_f32_16x16x32_bf16 v[20:23], v[148:151], v[208:211], v[20:23]
	v_mfma_f32_16x16x32_bf16 v[16:19], v[184:187], v[208:211], v[16:19]
	v_mfma_f32_16x16x32_bf16 v[16:19], v[180:183], v[204:207], v[16:19]
	v_mfma_f32_16x16x32_bf16 v[0:3], v[180:183], v[212:215], v[0:3]
	v_mfma_f32_16x16x32_bf16 v[0:3], v[184:187], v[216:219], v[0:3]
	v_mfma_f32_16x16x32_bf16 v[4:7], v[148:151], v[216:219], v[4:7]
	v_mfma_f32_16x16x32_bf16 v[4:7], v[144:147], v[212:215], v[4:7]
	v_mfma_f32_16x16x32_bf16 v[8:11], v[136:139], v[212:215], v[8:11]
	v_mfma_f32_16x16x32_bf16 v[8:11], v[140:143], v[216:219], v[8:11]
	v_mfma_f32_16x16x32_bf16 v[12:15], v[132:135], v[216:219], v[12:15]
	v_mfma_f32_16x16x32_bf16 v[12:15], v[128:131], v[212:215], v[12:15]
	s_barrier
	s_add_i32 s40, s40, 2
	s_add_u32 s38, s38, 0x1000
	s_addc_u32 s39, s39, 0
	s_add_u32 s28, s28, 0x100
	s_addc_u32 s29, s29, 0
	s_cmp_gt_u32 s40, 61
	s_cbranch_scc0 .LBB0_1202
	s_setprio 0

.LBB0_1434:
	s_ashr_i32 s19, s18, 31
	s_lshl_b64 s[20:21], s[18:19], 19
	s_add_u32 s20, s33, s20
	s_addc_u32 s21, s36, s21
	s_and_b64 s[22:23], s[4:5], exec
	s_cselect_b32 s1, s21, s25
	s_cselect_b32 s19, s20, s24
	s_ashr_i32 s22, s18, 4
	s_ashr_i32 s23, s22, 31
	s_lshl_b64 s[22:23], s[22:23], 11
	s_add_u32 s28, s37, s22
	s_addc_u32 s29, s38, s23
	s_ashr_i32 s17, s16, 31
	s_lshl_b64 s[22:23], s[16:17], 21
	s_add_u32 s22, s28, s22
	s_addc_u32 s23, s29, s23
	s_and_b64 s[28:29], s[4:5], exec
	s_cselect_b32 s17, s23, s27
	s_cselect_b32 s30, s22, s26
	s_add_u32 s24, s24, 0x40080
	s_addc_u32 s25, s25, 0
	s_add_u32 s31, s26, 0x100
	v_mov_b32_e32 v0, 0
	s_addc_u32 s34, s27, 0
	s_mov_b32 s35, -2
	s_waitcnt lgkmcnt(0)
	v_mov_b32_e32 v1, v0
	v_mov_b32_e32 v2, v0
	v_mov_b32_e32 v3, v0
	v_mov_b32_e32 v4, v0
	v_mov_b32_e32 v5, v0
	v_mov_b32_e32 v6, v0
	v_mov_b32_e32 v7, v0
	v_mov_b32_e32 v16, v0
	v_mov_b32_e32 v17, v0
	v_mov_b32_e32 v18, v0
	v_mov_b32_e32 v19, v0
	v_mov_b32_e32 v20, v0
	v_mov_b32_e32 v21, v0
	v_mov_b32_e32 v22, v0
	v_mov_b32_e32 v23, v0
	v_mov_b32_e32 v32, v0
	v_mov_b32_e32 v33, v0
	v_mov_b32_e32 v34, v0
	v_mov_b32_e32 v35, v0
	v_mov_b32_e32 v36, v0
	v_mov_b32_e32 v37, v0
	v_mov_b32_e32 v38, v0
	v_mov_b32_e32 v39, v0
	v_mov_b32_e32 v48, v0
	v_mov_b32_e32 v49, v0
	v_mov_b32_e32 v50, v0
	v_mov_b32_e32 v51, v0
	v_mov_b32_e32 v52, v0
	v_mov_b32_e32 v53, v0
	v_mov_b32_e32 v54, v0
	v_mov_b32_e32 v55, v0
	v_mov_b32_e32 v8, v0
	v_mov_b32_e32 v9, v0
	v_mov_b32_e32 v10, v0
	v_mov_b32_e32 v11, v0
	v_mov_b32_e32 v12, v0
	v_mov_b32_e32 v13, v0
	v_mov_b32_e32 v14, v0
	v_mov_b32_e32 v15, v0
	v_mov_b32_e32 v24, v0
	v_mov_b32_e32 v25, v0
	v_mov_b32_e32 v26, v0
	v_mov_b32_e32 v27, v0
	v_mov_b32_e32 v28, v0
	v_mov_b32_e32 v29, v0
	v_mov_b32_e32 v30, v0
	v_mov_b32_e32 v31, v0
	v_mov_b32_e32 v40, v0
	v_mov_b32_e32 v41, v0
	v_mov_b32_e32 v42, v0
	v_mov_b32_e32 v43, v0
	v_mov_b32_e32 v44, v0
	v_mov_b32_e32 v45, v0
	v_mov_b32_e32 v46, v0
	v_mov_b32_e32 v47, v0
	v_mov_b32_e32 v56, v0
	v_mov_b32_e32 v57, v0
	v_mov_b32_e32 v58, v0
	v_mov_b32_e32 v59, v0
	v_mov_b32_e32 v60, v0
	v_mov_b32_e32 v61, v0
	v_mov_b32_e32 v62, v0
	v_mov_b32_e32 v63, v0
	v_mov_b32_e32 v64, v0
	v_mov_b32_e32 v65, v0
	v_mov_b32_e32 v66, v0
	v_mov_b32_e32 v67, v0
	v_mov_b32_e32 v68, v0
	v_mov_b32_e32 v69, v0
	v_mov_b32_e32 v70, v0
	v_mov_b32_e32 v71, v0
	v_mov_b32_e32 v80, v0
	v_mov_b32_e32 v81, v0
	v_mov_b32_e32 v82, v0
	v_mov_b32_e32 v83, v0
	v_mov_b32_e32 v84, v0
	v_mov_b32_e32 v85, v0
	v_mov_b32_e32 v86, v0
	v_mov_b32_e32 v87, v0
	v_mov_b32_e32 v96, v0
	v_mov_b32_e32 v97, v0
	v_mov_b32_e32 v98, v0
	v_mov_b32_e32 v99, v0
	v_mov_b32_e32 v100, v0
	v_mov_b32_e32 v101, v0
	v_mov_b32_e32 v102, v0
	v_mov_b32_e32 v103, v0
	v_mov_b32_e32 v112, v0
	v_mov_b32_e32 v113, v0
	v_mov_b32_e32 v114, v0
	v_mov_b32_e32 v115, v0
	v_mov_b32_e32 v116, v0
	v_mov_b32_e32 v117, v0
	v_mov_b32_e32 v118, v0
	v_mov_b32_e32 v119, v0
	v_mov_b32_e32 v72, v0
	v_mov_b32_e32 v73, v0
	v_mov_b32_e32 v74, v0
	v_mov_b32_e32 v75, v0
	v_mov_b32_e32 v76, v0
	v_mov_b32_e32 v77, v0
	v_mov_b32_e32 v78, v0
	v_mov_b32_e32 v79, v0
	v_mov_b32_e32 v88, v0
	v_mov_b32_e32 v89, v0
	v_mov_b32_e32 v90, v0
	v_mov_b32_e32 v91, v0
	v_mov_b32_e32 v92, v0
	v_mov_b32_e32 v93, v0
	v_mov_b32_e32 v94, v0
	v_mov_b32_e32 v95, v0
	v_mov_b32_e32 v104, v0
	v_mov_b32_e32 v105, v0
	v_mov_b32_e32 v106, v0
	v_mov_b32_e32 v107, v0
	v_mov_b32_e32 v108, v0
	v_mov_b32_e32 v109, v0
	v_mov_b32_e32 v110, v0
	v_mov_b32_e32 v111, v0
	v_mov_b32_e32 v120, v0
	v_mov_b32_e32 v121, v0
	v_mov_b32_e32 v122, v0
	v_mov_b32_e32 v123, v0
	v_mov_b32_e32 v124, v0
	v_mov_b32_e32 v125, v0
	v_mov_b32_e32 v126, v0
	v_mov_b32_e32 v127, v0
	s_and_b64 vcc, exec, s[8:9]
	s_cbranch_vccnz .Lsprio_P7
	s_setprio 1

.LBB0_1435:
	ds_read_b128 v[128:131], v180
	ds_read_b128 v[132:135], v180 offset:1024
	ds_read_b128 v[136:139], v180 offset:2048
	ds_read_b128 v[140:143], v180 offset:3072
	ds_read_b128 v[144:147], v181
	ds_read_b128 v[148:151], v181 offset:1024
	ds_read_b128 v[170:173], v181 offset:2048
	ds_read_b128 v[174:177], v181 offset:3072
	s_add_u32 s26, s24, 0xfffc0080
	s_addc_u32 s27, s25, -1
	s_cmp_eq_u32 s35, 12
	s_cselect_b32 s29, s1, s27
	s_cselect_b32 s28, s19, s26
	s_cselect_b32 s27, s17, s34
	s_cselect_b32 s26, s30, s31
	v_lshl_add_u64 v[184:185], s[24:25], 0, v[162:163]
	s_add_i32 m0, s40, 0xc000
	s_nop 0
	global_load_lds_dwordx4 v[184:185], off
	v_lshl_add_u64 v[184:185], s[24:25], 0, v[164:165]
	s_add_i32 m0, s40, 0xe000
	s_nop 0
	global_load_lds_dwordx4 v[184:185], off
	ds_read_b128 v[184:187], v182
	ds_read_b128 v[188:191], v182 offset:1024
	ds_read_b128 v[192:195], v182 offset:2048
	ds_read_b128 v[196:199], v182 offset:3072
	ds_read_b128 v[200:203], v182 offset:4096
	ds_read_b128 v[204:207], v182 offset:5120
	ds_read_b128 v[208:211], v182 offset:6144
	ds_read_b128 v[212:215], v182 offset:7168
	s_waitcnt vmcnt(8)
	s_waitcnt lgkmcnt(0)
	s_barrier
	v_mfma_f32_16x16x32_bf16 v[124:127], v[128:131], v[184:187], v[124:127]
	v_mfma_f32_16x16x32_bf16 v[124:127], v[132:135], v[188:191], v[124:127]
	v_mfma_f32_16x16x32_bf16 v[120:123], v[140:143], v[188:191], v[120:123]
	v_mfma_f32_16x16x32_bf16 v[120:123], v[136:139], v[184:187], v[120:123]
	v_mfma_f32_16x16x32_bf16 v[116:119], v[144:147], v[184:187], v[116:119]
	v_mfma_f32_16x16x32_bf16 v[116:119], v[148:151], v[188:191], v[116:119]
	v_mfma_f32_16x16x32_bf16 v[112:115], v[174:177], v[188:191], v[112:115]
	v_mfma_f32_16x16x32_bf16 v[112:115], v[170:173], v[184:187], v[112:115]
	v_mfma_f32_16x16x32_bf16 v[96:99], v[170:173], v[192:195], v[96:99]
	v_mfma_f32_16x16x32_bf16 v[96:99], v[174:177], v[196:199], v[96:99]
	v_mfma_f32_16x16x32_bf16 v[100:103], v[148:151], v[196:199], v[100:103]
	v_mfma_f32_16x16x32_bf16 v[100:103], v[144:147], v[192:195], v[100:103]
	v_mfma_f32_16x16x32_bf16 v[104:107], v[136:139], v[192:195], v[104:107]
	v_mfma_f32_16x16x32_bf16 v[104:107], v[140:143], v[196:199], v[104:107]
	v_mfma_f32_16x16x32_bf16 v[108:111], v[132:135], v[196:199], v[108:111]
	v_mfma_f32_16x16x32_bf16 v[108:111], v[128:131], v[192:195], v[108:111]
	v_mfma_f32_16x16x32_bf16 v[92:95], v[128:131], v[200:203], v[92:95]
	v_mfma_f32_16x16x32_bf16 v[92:95], v[132:135], v[204:207], v[92:95]
	v_mfma_f32_16x16x32_bf16 v[88:91], v[140:143], v[204:207], v[88:91]
	v_mfma_f32_16x16x32_bf16 v[88:91], v[136:139], v[200:203], v[88:91]
	v_mfma_f32_16x16x32_bf16 v[84:87], v[144:147], v[200:203], v[84:87]
	v_mfma_f32_16x16x32_bf16 v[84:87], v[148:151], v[204:207], v[84:87]
	v_mfma_f32_16x16x32_bf16 v[80:83], v[174:177], v[204:207], v[80:83]
	v_mfma_f32_16x16x32_bf16 v[80:83], v[170:173], v[200:203], v[80:83]
	v_mfma_f32_16x16x32_bf16 v[64:67], v[170:173], v[208:211], v[64:67]
	v_mfma_f32_16x16x32_bf16 v[64:67], v[174:177], v[212:215], v[64:67]
	v_mfma_f32_16x16x32_bf16 v[68:71], v[148:151], v[212:215], v[68:71]
	v_mfma_f32_16x16x32_bf16 v[68:71], v[144:147], v[208:211], v[68:71]
	v_mfma_f32_16x16x32_bf16 v[72:75], v[136:139], v[208:211], v[72:75]
	v_mfma_f32_16x16x32_bf16 v[72:75], v[140:143], v[212:215], v[72:75]
	v_mfma_f32_16x16x32_bf16 v[76:79], v[132:135], v[212:215], v[76:79]
	v_mfma_f32_16x16x32_bf16 v[76:79], v[128:131], v[208:211], v[76:79]
	s_barrier
	s_add_i32 s54, s50, s39
	v_lshl_add_u64 v[216:217], s[26:27], 0, v[154:155]
	s_mov_b32 m0, s54
	v_lshl_add_u64 v[218:219], s[26:27], 0, v[158:159]
	global_load_lds_dwordx4 v[216:217], off
	s_add_i32 m0, s54, 0x2000
	s_add_u32 s54, s26, 0x100000
	s_addc_u32 s55, s27, 0
	s_add_i32 s56, s51, s39
	global_load_lds_dwordx4 v[218:219], off
	v_lshl_add_u64 v[184:185], s[54:55], 0, v[154:155]
	s_mov_b32 m0, s56
	v_lshl_add_u64 v[220:221], s[28:29], 0, v[152:153]
	global_load_lds_dwordx4 v[184:185], off
	v_lshl_add_u64 v[184:185], s[54:55], 0, v[158:159]
	s_add_i32 m0, s56, 0x2000
	v_lshl_add_u64 v[222:223], s[28:29], 0, v[156:157]
	global_load_lds_dwordx4 v[184:185], off
	s_mov_b32 m0, s40
	s_nop 0
	global_load_lds_dwordx4 v[220:221], off
	s_mov_b32 m0, s41
	s_nop 0
	global_load_lds_dwordx4 v[222:223], off
	ds_read_b128 v[184:187], v182 offset:16384
	ds_read_b128 v[188:191], v182 offset:17408
	ds_read_b128 v[192:195], v182 offset:18432
	ds_read_b128 v[196:199], v182 offset:19456
	ds_read_b128 v[200:203], v182 offset:20480
	ds_read_b128 v[204:207], v182 offset:21504
	ds_read_b128 v[208:211], v182 offset:22528
	ds_read_b128 v[212:215], v182 offset:23552
	s_waitcnt vmcnt(8)
	s_waitcnt lgkmcnt(0)
	s_barrier
	v_mfma_f32_16x16x32_bf16 v[60:63], v[128:131], v[184:187], v[60:63]
	v_mfma_f32_16x16x32_bf16 v[60:63], v[132:135], v[188:191], v[60:63]
	v_mfma_f32_16x16x32_bf16 v[56:59], v[140:143], v[188:191], v[56:59]
	v_mfma_f32_16x16x32_bf16 v[56:59], v[136:139], v[184:187], v[56:59]
	v_mfma_f32_16x16x32_bf16 v[52:55], v[144:147], v[184:187], v[52:55]
	v_mfma_f32_16x16x32_bf16 v[52:55], v[148:151], v[188:191], v[52:55]
	v_mfma_f32_16x16x32_bf16 v[48:51], v[174:177], v[188:191], v[48:51]
	v_mfma_f32_16x16x32_bf16 v[48:51], v[170:173], v[184:187], v[48:51]
	v_mfma_f32_16x16x32_bf16 v[32:35], v[170:173], v[192:195], v[32:35]
	v_mfma_f32_16x16x32_bf16 v[32:35], v[174:177], v[196:199], v[32:35]
	v_mfma_f32_16x16x32_bf16 v[36:39], v[148:151], v[196:199], v[36:39]
	v_mfma_f32_16x16x32_bf16 v[36:39], v[144:147], v[192:195], v[36:39]
	v_mfma_f32_16x16x32_bf16 v[40:43], v[136:139], v[192:195], v[40:43]
	v_mfma_f32_16x16x32_bf16 v[40:43], v[140:143], v[196:199], v[40:43]
	v_mfma_f32_16x16x32_bf16 v[44:47], v[132:135], v[196:199], v[44:47]
	v_mfma_f32_16x16x32_bf16 v[44:47], v[128:131], v[192:195], v[44:47]
	v_mfma_f32_16x16x32_bf16 v[28:31], v[128:131], v[200:203], v[28:31]
	v_mfma_f32_16x16x32_bf16 v[28:31], v[132:135], v[204:207], v[28:31]
	v_mfma_f32_16x16x32_bf16 v[24:27], v[140:143], v[204:207], v[24:27]
	v_mfma_f32_16x16x32_bf16 v[24:27], v[136:139], v[200:203], v[24:27]
	v_mfma_f32_16x16x32_bf16 v[20:23], v[144:147], v[200:203], v[20:23]
	v_mfma_f32_16x16x32_bf16 v[20:23], v[148:151], v[204:207], v[20:23]
	v_mfma_f32_16x16x32_bf16 v[16:19], v[174:177], v[204:207], v[16:19]
	v_mfma_f32_16x16x32_bf16 v[16:19], v[170:173], v[200:203], v[16:19]
	v_mfma_f32_16x16x32_bf16 v[0:3], v[170:173], v[208:211], v[0:3]
	v_mfma_f32_16x16x32_bf16 v[0:3], v[174:177], v[212:215], v[0:3]
	v_mfma_f32_16x16x32_bf16 v[4:7], v[148:151], v[212:215], v[4:7]
	v_mfma_f32_16x16x32_bf16 v[4:7], v[144:147], v[208:211], v[4:7]
	v_mfma_f32_16x16x32_bf16 v[8:11], v[136:139], v[208:211], v[8:11]
	v_mfma_f32_16x16x32_bf16 v[8:11], v[140:143], v[212:215], v[8:11]
	v_mfma_f32_16x16x32_bf16 v[12:15], v[132:135], v[212:215], v[12:15]
	v_mfma_f32_16x16x32_bf16 v[12:15], v[128:131], v[208:211], v[12:15]
	s_barrier
	s_add_i32 s54, 0, 0x18000
	s_add_i32 s55, 0, 0x1c000
	v_add_u32_e32 v140, s54, v178
	v_add_u32_e32 v174, s55, v178
	ds_read_b128 v[128:131], v140
	ds_read_b128 v[132:135], v140 offset:1024
	ds_read_b128 v[136:139], v140 offset:2048
	ds_read_b128 v[140:143], v140 offset:3072
	ds_read_b128 v[144:147], v174
	ds_read_b128 v[148:151], v174 offset:1024
	ds_read_b128 v[170:173], v174 offset:2048
	ds_read_b128 v[174:177], v174 offset:3072
	s_add_u32 s28, s28, 0x40000
	s_addc_u32 s29, s29, 0
	s_mov_b32 m0, s42
	v_lshl_add_u64 v[184:185], s[28:29], 0, v[152:153]
	global_load_lds_dwordx4 v[184:185], off
	v_lshl_add_u64 v[184:185], s[28:29], 0, v[156:157]
	s_mov_b32 m0, s43
	s_nop 0
	global_load_lds_dwordx4 v[184:185], off
	ds_read_b128 v[184:187], v182 offset:32768
	ds_read_b128 v[188:191], v182 offset:33792
	ds_read_b128 v[192:195], v182 offset:34816
	ds_read_b128 v[196:199], v182 offset:35840
	ds_read_b128 v[200:203], v182 offset:36864
	ds_read_b128 v[204:207], v182 offset:37888
	ds_read_b128 v[208:211], v182 offset:38912
	ds_read_b128 v[212:215], v182 offset:39936
	s_waitcnt vmcnt(8)
	s_waitcnt lgkmcnt(0)
	s_barrier
	v_mfma_f32_16x16x32_bf16 v[124:127], v[128:131], v[184:187], v[124:127]
	v_mfma_f32_16x16x32_bf16 v[124:127], v[132:135], v[188:191], v[124:127]
	v_mfma_f32_16x16x32_bf16 v[120:123], v[140:143], v[188:191], v[120:123]
	v_mfma_f32_16x16x32_bf16 v[120:123], v[136:139], v[184:187], v[120:123]
	v_mfma_f32_16x16x32_bf16 v[116:119], v[144:147], v[184:187], v[116:119]
	v_mfma_f32_16x16x32_bf16 v[116:119], v[148:151], v[188:191], v[116:119]
	v_mfma_f32_16x16x32_bf16 v[112:115], v[174:177], v[188:191], v[112:115]
	v_mfma_f32_16x16x32_bf16 v[112:115], v[170:173], v[184:187], v[112:115]
	v_mfma_f32_16x16x32_bf16 v[96:99], v[170:173], v[192:195], v[96:99]
	v_mfma_f32_16x16x32_bf16 v[96:99], v[174:177], v[196:199], v[96:99]
	v_mfma_f32_16x16x32_bf16 v[100:103], v[148:151], v[196:199], v[100:103]
	v_mfma_f32_16x16x32_bf16 v[100:103], v[144:147], v[192:195], v[100:103]
	v_mfma_f32_16x16x32_bf16 v[104:107], v[136:139], v[192:195], v[104:107]
	v_mfma_f32_16x16x32_bf16 v[104:107], v[140:143], v[196:199], v[104:107]
	v_mfma_f32_16x16x32_bf16 v[108:111], v[132:135], v[196:199], v[108:111]
	v_mfma_f32_16x16x32_bf16 v[108:111], v[128:131], v[192:195], v[108:111]
	v_mfma_f32_16x16x32_bf16 v[92:95], v[128:131], v[200:203], v[92:95]
	v_mfma_f32_16x16x32_bf16 v[92:95], v[132:135], v[204:207], v[92:95]
	v_mfma_f32_16x16x32_bf16 v[88:91], v[140:143], v[204:207], v[88:91]
	v_mfma_f32_16x16x32_bf16 v[88:91], v[136:139], v[200:203], v[88:91]
	v_mfma_f32_16x16x32_bf16 v[84:87], v[144:147], v[200:203], v[84:87]
	v_mfma_f32_16x16x32_bf16 v[84:87], v[148:151], v[204:207], v[84:87]
	v_mfma_f32_16x16x32_bf16 v[80:83], v[174:177], v[204:207], v[80:83]
	v_mfma_f32_16x16x32_bf16 v[80:83], v[170:173], v[200:203], v[80:83]
	v_mfma_f32_16x16x32_bf16 v[64:67], v[170:173], v[208:211], v[64:67]
	v_mfma_f32_16x16x32_bf16 v[64:67], v[174:177], v[212:215], v[64:67]
	v_mfma_f32_16x16x32_bf16 v[68:71], v[148:151], v[212:215], v[68:71]
	v_mfma_f32_16x16x32_bf16 v[68:71], v[144:147], v[208:211], v[68:71]
	v_mfma_f32_16x16x32_bf16 v[72:75], v[136:139], v[208:211], v[72:75]
	v_mfma_f32_16x16x32_bf16 v[72:75], v[140:143], v[212:215], v[72:75]
	v_mfma_f32_16x16x32_bf16 v[76:79], v[132:135], v[212:215], v[76:79]
	v_mfma_f32_16x16x32_bf16 v[76:79], v[128:131], v[208:211], v[76:79]
	s_barrier
	s_add_i32 s28, s54, s39
	v_lshl_add_u64 v[184:185], v[216:217], 0, s[14:15]
	s_mov_b32 m0, s28
	s_nop 0
	global_load_lds_dwordx4 v[184:185], off
	s_add_i32 m0, s28, 0x2000
	s_add_u32 s26, s26, 0x100080
	v_lshl_add_u64 v[184:185], v[218:219], 0, s[14:15]
	s_addc_u32 s27, s27, 0
	s_add_i32 s28, s55, s39
	global_load_lds_dwordx4 v[184:185], off
	v_lshl_add_u64 v[184:185], s[26:27], 0, v[154:155]
	s_mov_b32 m0, s28
	s_nop 0
	global_load_lds_dwordx4 v[184:185], off
	v_lshl_add_u64 v[184:185], s[26:27], 0, v[158:159]
	s_add_i32 m0, s28, 0x2000
	s_nop 0
	global_load_lds_dwordx4 v[184:185], off
	v_lshl_add_u64 v[184:185], v[220:221], 0, s[14:15]
	s_mov_b32 m0, s45
	s_nop 0
	global_load_lds_dwordx4 v[184:185], off
	v_lshl_add_u64 v[184:185], v[222:223], 0, s[14:15]
	s_mov_b32 m0, s46
	s_nop 0
	global_load_lds_dwordx4 v[184:185], off
	ds_read_b128 v[184:187], v182 offset:49152
	ds_read_b128 v[188:191], v182 offset:50176
	ds_read_b128 v[192:195], v182 offset:51200
	ds_read_b128 v[196:199], v182 offset:52224
	ds_read_b128 v[200:203], v182 offset:53248
	ds_read_b128 v[204:207], v182 offset:54272
	ds_read_b128 v[208:211], v182 offset:55296
	ds_read_b128 v[212:215], v182 offset:56320
	s_waitcnt vmcnt(8)
	s_waitcnt lgkmcnt(0)
	s_barrier
	v_mfma_f32_16x16x32_bf16 v[60:63], v[128:131], v[184:187], v[60:63]
	v_mfma_f32_16x16x32_bf16 v[60:63], v[132:135], v[188:191], v[60:63]
	v_mfma_f32_16x16x32_bf16 v[56:59], v[140:143], v[188:191], v[56:59]
	v_mfma_f32_16x16x32_bf16 v[56:59], v[136:139], v[184:187], v[56:59]
	v_mfma_f32_16x16x32_bf16 v[52:55], v[144:147], v[184:187], v[52:55]
	v_mfma_f32_16x16x32_bf16 v[52:55], v[148:151], v[188:191], v[52:55]
	v_mfma_f32_16x16x32_bf16 v[48:51], v[174:177], v[188:191], v[48:51]
	v_mfma_f32_16x16x32_bf16 v[48:51], v[170:173], v[184:187], v[48:51]
	v_mfma_f32_16x16x32_bf16 v[32:35], v[170:173], v[192:195], v[32:35]
	v_mfma_f32_16x16x32_bf16 v[32:35], v[174:177], v[196:199], v[32:35]
	v_mfma_f32_16x16x32_bf16 v[36:39], v[148:151], v[196:199], v[36:39]
	v_mfma_f32_16x16x32_bf16 v[36:39], v[144:147], v[192:195], v[36:39]
	v_mfma_f32_16x16x32_bf16 v[40:43], v[136:139], v[192:195], v[40:43]
	v_mfma_f32_16x16x32_bf16 v[40:43], v[140:143], v[196:199], v[40:43]
	v_mfma_f32_16x16x32_bf16 v[44:47], v[132:135], v[196:199], v[44:47]
	v_mfma_f32_16x16x32_bf16 v[44:47], v[128:131], v[192:195], v[44:47]
	v_mfma_f32_16x16x32_bf16 v[28:31], v[128:131], v[200:203], v[28:31]
	v_mfma_f32_16x16x32_bf16 v[28:31], v[132:135], v[204:207], v[28:31]
	v_mfma_f32_16x16x32_bf16 v[24:27], v[140:143], v[204:207], v[24:27]
	v_mfma_f32_16x16x32_bf16 v[24:27], v[136:139], v[200:203], v[24:27]
	v_mfma_f32_16x16x32_bf16 v[20:23], v[144:147], v[200:203], v[20:23]
	v_mfma_f32_16x16x32_bf16 v[20:23], v[148:151], v[204:207], v[20:23]
	v_mfma_f32_16x16x32_bf16 v[16:19], v[174:177], v[204:207], v[16:19]
	v_mfma_f32_16x16x32_bf16 v[16:19], v[170:173], v[200:203], v[16:19]
	v_mfma_f32_16x16x32_bf16 v[0:3], v[170:173], v[208:211], v[0:3]
	v_mfma_f32_16x16x32_bf16 v[0:3], v[174:177], v[212:215], v[0:3]
	v_mfma_f32_16x16x32_bf16 v[4:7], v[148:151], v[212:215], v[4:7]
	v_mfma_f32_16x16x32_bf16 v[4:7], v[144:147], v[208:211], v[4:7]
	v_mfma_f32_16x16x32_bf16 v[8:11], v[136:139], v[208:211], v[8:11]
	v_mfma_f32_16x16x32_bf16 v[8:11], v[140:143], v[212:215], v[8:11]
	v_mfma_f32_16x16x32_bf16 v[12:15], v[132:135], v[212:215], v[12:15]
	v_mfma_f32_16x16x32_bf16 v[12:15], v[128:131], v[208:211], v[12:15]
	s_barrier
	s_add_i32 s35, s35, 2
	s_add_u32 s24, s24, 0x100
	s_addc_u32 s25, s25, 0
	s_add_u32 s31, s31, 0x100
	s_addc_u32 s34, s34, 0
	s_cmp_gt_u32 s35, 13
	s_cbranch_scc0 .LBB0_1435
	s_setprio 0

.LBB0_1542:
	s_ashr_i32 s13, s12, 31
	s_lshl_b64 s[14:15], s[12:13], 21
	s_add_u32 s14, s31, s14
	s_addc_u32 s15, s33, s15
	s_and_b64 s[16:17], s[2:3], exec
	s_cselect_b32 s13, s15, s21
	s_cselect_b32 s50, s14, s20
	s_ashr_i32 s11, s10, 31
	s_lshl_b64 s[16:17], s[10:11], 21
	s_add_u32 s16, s34, s16
	s_addc_u32 s17, s35, s17
	s_and_b64 s[24:25], s[2:3], exec
	s_cselect_b32 s11, s17, s23
	s_cselect_b32 s51, s16, s22
	s_add_u32 s52, s22, 0x1000
	v_mov_b32_e32 v0, 0
	s_addc_u32 s53, s23, 0
	s_mov_b32 s54, -2
	v_mov_b32_e32 v1, v0
	v_mov_b32_e32 v2, v0
	v_mov_b32_e32 v3, v0
	v_mov_b32_e32 v4, v0
	v_mov_b32_e32 v5, v0
	v_mov_b32_e32 v6, v0
	v_mov_b32_e32 v7, v0
	v_mov_b32_e32 v16, v0
	v_mov_b32_e32 v17, v0
	v_mov_b32_e32 v18, v0
	v_mov_b32_e32 v19, v0
	v_mov_b32_e32 v20, v0
	v_mov_b32_e32 v21, v0
	v_mov_b32_e32 v22, v0
	v_mov_b32_e32 v23, v0
	v_mov_b32_e32 v32, v0
	v_mov_b32_e32 v33, v0
	v_mov_b32_e32 v34, v0
	v_mov_b32_e32 v35, v0
	v_mov_b32_e32 v36, v0
	v_mov_b32_e32 v37, v0
	v_mov_b32_e32 v38, v0
	v_mov_b32_e32 v39, v0
	v_mov_b32_e32 v48, v0
	v_mov_b32_e32 v49, v0
	v_mov_b32_e32 v50, v0
	v_mov_b32_e32 v51, v0
	v_mov_b32_e32 v52, v0
	v_mov_b32_e32 v53, v0
	v_mov_b32_e32 v54, v0
	v_mov_b32_e32 v55, v0
	v_mov_b32_e32 v8, v0
	v_mov_b32_e32 v9, v0
	v_mov_b32_e32 v10, v0
	v_mov_b32_e32 v11, v0
	v_mov_b32_e32 v12, v0
	v_mov_b32_e32 v13, v0
	v_mov_b32_e32 v14, v0
	v_mov_b32_e32 v15, v0
	v_mov_b32_e32 v24, v0
	v_mov_b32_e32 v25, v0
	v_mov_b32_e32 v26, v0
	v_mov_b32_e32 v27, v0
	v_mov_b32_e32 v28, v0
	v_mov_b32_e32 v29, v0
	v_mov_b32_e32 v30, v0
	v_mov_b32_e32 v31, v0
	v_mov_b32_e32 v40, v0
	v_mov_b32_e32 v41, v0
	v_mov_b32_e32 v42, v0
	v_mov_b32_e32 v43, v0
	v_mov_b32_e32 v44, v0
	v_mov_b32_e32 v45, v0
	v_mov_b32_e32 v46, v0
	v_mov_b32_e32 v47, v0
	v_mov_b32_e32 v56, v0
	v_mov_b32_e32 v57, v0
	v_mov_b32_e32 v58, v0
	v_mov_b32_e32 v59, v0
	v_mov_b32_e32 v60, v0
	v_mov_b32_e32 v61, v0
	v_mov_b32_e32 v62, v0
	v_mov_b32_e32 v63, v0
	v_mov_b32_e32 v64, v0
	v_mov_b32_e32 v65, v0
	v_mov_b32_e32 v66, v0
	v_mov_b32_e32 v67, v0
	v_mov_b32_e32 v68, v0
	v_mov_b32_e32 v69, v0
	v_mov_b32_e32 v70, v0
	v_mov_b32_e32 v71, v0
	v_mov_b32_e32 v80, v0
	v_mov_b32_e32 v81, v0
	v_mov_b32_e32 v82, v0
	v_mov_b32_e32 v83, v0
	v_mov_b32_e32 v84, v0
	v_mov_b32_e32 v85, v0
	v_mov_b32_e32 v86, v0
	v_mov_b32_e32 v87, v0
	v_mov_b32_e32 v96, v0
	v_mov_b32_e32 v97, v0
	v_mov_b32_e32 v98, v0
	v_mov_b32_e32 v99, v0
	v_mov_b32_e32 v100, v0
	v_mov_b32_e32 v101, v0
	v_mov_b32_e32 v102, v0
	v_mov_b32_e32 v103, v0
	v_mov_b32_e32 v112, v0
	v_mov_b32_e32 v113, v0
	v_mov_b32_e32 v114, v0
	v_mov_b32_e32 v115, v0
	v_mov_b32_e32 v116, v0
	v_mov_b32_e32 v117, v0
	v_mov_b32_e32 v118, v0
	v_mov_b32_e32 v119, v0
	v_mov_b32_e32 v72, v0
	v_mov_b32_e32 v73, v0
	v_mov_b32_e32 v74, v0
	v_mov_b32_e32 v75, v0
	v_mov_b32_e32 v76, v0
	v_mov_b32_e32 v77, v0
	v_mov_b32_e32 v78, v0
	v_mov_b32_e32 v79, v0
	v_mov_b32_e32 v88, v0
	v_mov_b32_e32 v89, v0
	v_mov_b32_e32 v90, v0
	v_mov_b32_e32 v91, v0
	v_mov_b32_e32 v92, v0
	v_mov_b32_e32 v93, v0
	v_mov_b32_e32 v94, v0
	v_mov_b32_e32 v95, v0
	v_mov_b32_e32 v104, v0
	v_mov_b32_e32 v105, v0
	v_mov_b32_e32 v106, v0
	v_mov_b32_e32 v107, v0
	v_mov_b32_e32 v108, v0
	v_mov_b32_e32 v109, v0
	v_mov_b32_e32 v110, v0
	v_mov_b32_e32 v111, v0
	v_mov_b32_e32 v120, v0
	v_mov_b32_e32 v121, v0
	v_mov_b32_e32 v122, v0
	v_mov_b32_e32 v123, v0
	v_mov_b32_e32 v124, v0
	v_mov_b32_e32 v125, v0
	v_mov_b32_e32 v126, v0
	v_mov_b32_e32 v127, v0
	s_and_b64 vcc, exec, s[4:5]
	s_cbranch_vccnz .Lsprio_P8
	s_setprio 1

.LBB0_1543:
	ds_read_b128 v[128:131], v167
	ds_read_b128 v[154:157], v167 offset:1024
	ds_read_b128 v[172:175], v167 offset:2048
	ds_read_b128 v[176:179], v167 offset:3072
	ds_read_b128 v[180:183], v168
	ds_read_b128 v[184:187], v168 offset:1024
	ds_read_b128 v[188:191], v168 offset:2048
	ds_read_b128 v[192:195], v168 offset:3072
	s_add_u32 s22, s20, 0x1000
	s_addc_u32 s23, s21, 0
	s_cmp_eq_u32 s54, 60
	s_cselect_b32 s27, s13, s23
	s_cselect_b32 s26, s50, s22
	s_cselect_b32 s25, s11, s53
	s_cselect_b32 s24, s51, s52
	v_lshl_add_u64 v[160:161], s[20:21], 0, v[144:145]
	s_add_i32 m0, s19, 0xc000
	s_nop 0
	global_load_lds_dwordx4 v[160:161], off
	v_lshl_add_u64 v[160:161], s[20:21], 0, v[146:147]
	s_add_i32 m0, s19, 0xe000
	s_nop 0
	global_load_lds_dwordx4 v[160:161], off
	ds_read_b128 v[196:199], v169
	ds_read_b128 v[200:203], v169 offset:1024
	ds_read_b128 v[204:207], v169 offset:2048
	ds_read_b128 v[208:211], v169 offset:3072
	ds_read_b128 v[212:215], v169 offset:4096
	ds_read_b128 v[216:219], v169 offset:5120
	ds_read_b128 v[220:223], v169 offset:6144
	ds_read_b128 v[224:227], v169 offset:7168
	s_waitcnt vmcnt(8)
	s_waitcnt lgkmcnt(0)
	s_barrier
	v_mfma_f32_16x16x32_bf16 v[124:127], v[128:131], v[196:199], v[124:127]
	v_mfma_f32_16x16x32_bf16 v[124:127], v[154:157], v[200:203], v[124:127]
	v_mfma_f32_16x16x32_bf16 v[120:123], v[176:179], v[200:203], v[120:123]
	v_mfma_f32_16x16x32_bf16 v[120:123], v[172:175], v[196:199], v[120:123]
	v_mfma_f32_16x16x32_bf16 v[116:119], v[180:183], v[196:199], v[116:119]
	v_mfma_f32_16x16x32_bf16 v[116:119], v[184:187], v[200:203], v[116:119]
	v_mfma_f32_16x16x32_bf16 v[112:115], v[192:195], v[200:203], v[112:115]
	v_mfma_f32_16x16x32_bf16 v[112:115], v[188:191], v[196:199], v[112:115]
	v_mfma_f32_16x16x32_bf16 v[96:99], v[188:191], v[204:207], v[96:99]
	v_mfma_f32_16x16x32_bf16 v[96:99], v[192:195], v[208:211], v[96:99]
	v_mfma_f32_16x16x32_bf16 v[100:103], v[184:187], v[208:211], v[100:103]
	v_mfma_f32_16x16x32_bf16 v[100:103], v[180:183], v[204:207], v[100:103]
	v_mfma_f32_16x16x32_bf16 v[104:107], v[172:175], v[204:207], v[104:107]
	v_mfma_f32_16x16x32_bf16 v[104:107], v[176:179], v[208:211], v[104:107]
	v_mfma_f32_16x16x32_bf16 v[108:111], v[154:157], v[208:211], v[108:111]
	v_mfma_f32_16x16x32_bf16 v[108:111], v[128:131], v[204:207], v[108:111]
	v_mfma_f32_16x16x32_bf16 v[92:95], v[128:131], v[212:215], v[92:95]
	v_mfma_f32_16x16x32_bf16 v[92:95], v[154:157], v[216:219], v[92:95]
	v_mfma_f32_16x16x32_bf16 v[88:91], v[176:179], v[216:219], v[88:91]
	v_mfma_f32_16x16x32_bf16 v[88:91], v[172:175], v[212:215], v[88:91]
	v_mfma_f32_16x16x32_bf16 v[84:87], v[180:183], v[212:215], v[84:87]
	v_mfma_f32_16x16x32_bf16 v[84:87], v[184:187], v[216:219], v[84:87]
	v_mfma_f32_16x16x32_bf16 v[80:83], v[192:195], v[216:219], v[80:83]
	v_mfma_f32_16x16x32_bf16 v[80:83], v[188:191], v[212:215], v[80:83]
	v_mfma_f32_16x16x32_bf16 v[64:67], v[188:191], v[220:223], v[64:67]
	v_mfma_f32_16x16x32_bf16 v[64:67], v[192:195], v[224:227], v[64:67]
	v_mfma_f32_16x16x32_bf16 v[68:71], v[184:187], v[224:227], v[68:71]
	v_mfma_f32_16x16x32_bf16 v[68:71], v[180:183], v[220:223], v[68:71]
	v_mfma_f32_16x16x32_bf16 v[72:75], v[172:175], v[220:223], v[72:75]
	v_mfma_f32_16x16x32_bf16 v[72:75], v[176:179], v[224:227], v[72:75]
	v_mfma_f32_16x16x32_bf16 v[76:79], v[154:157], v[224:227], v[76:79]
	v_mfma_f32_16x16x32_bf16 v[76:79], v[128:131], v[220:223], v[76:79]
	s_barrier
	s_add_i32 s20, s45, s30
	v_lshl_add_u64 v[160:161], s[24:25], 0, v[134:135]
	s_mov_b32 m0, s20
	v_lshl_add_u64 v[164:165], s[24:25], 0, v[138:139]
	global_load_lds_dwordx4 v[160:161], off
	s_add_i32 m0, s20, 0x2000
	s_add_u32 s20, s24, 0x100000
	s_addc_u32 s21, s25, 0
	s_add_i32 s55, s46, s30
	global_load_lds_dwordx4 v[164:165], off
	v_lshl_add_u64 v[196:197], s[20:21], 0, v[134:135]
	s_mov_b32 m0, s55
	v_lshl_add_u64 v[228:229], s[26:27], 0, v[132:133]
	global_load_lds_dwordx4 v[196:197], off
	v_lshl_add_u64 v[196:197], s[20:21], 0, v[138:139]
	s_add_i32 m0, s55, 0x2000
	v_lshl_add_u64 v[230:231], s[26:27], 0, v[136:137]
	global_load_lds_dwordx4 v[196:197], off
	s_mov_b32 m0, s19
	s_nop 0
	global_load_lds_dwordx4 v[228:229], off
	s_mov_b32 m0, s36
	s_nop 0
	global_load_lds_dwordx4 v[230:231], off
	ds_read_b128 v[196:199], v169 offset:16384
	ds_read_b128 v[200:203], v169 offset:17408
	ds_read_b128 v[204:207], v169 offset:18432
	ds_read_b128 v[208:211], v169 offset:19456
	ds_read_b128 v[212:215], v169 offset:20480
	ds_read_b128 v[216:219], v169 offset:21504
	ds_read_b128 v[220:223], v169 offset:22528
	ds_read_b128 v[224:227], v169 offset:23552
	s_waitcnt vmcnt(8)
	s_waitcnt lgkmcnt(0)
	s_barrier
	v_mfma_f32_16x16x32_bf16 v[60:63], v[128:131], v[196:199], v[60:63]
	v_mfma_f32_16x16x32_bf16 v[60:63], v[154:157], v[200:203], v[60:63]
	v_mfma_f32_16x16x32_bf16 v[56:59], v[176:179], v[200:203], v[56:59]
	v_mfma_f32_16x16x32_bf16 v[56:59], v[172:175], v[196:199], v[56:59]
	v_mfma_f32_16x16x32_bf16 v[52:55], v[180:183], v[196:199], v[52:55]
	v_mfma_f32_16x16x32_bf16 v[52:55], v[184:187], v[200:203], v[52:55]
	v_mfma_f32_16x16x32_bf16 v[48:51], v[192:195], v[200:203], v[48:51]
	v_mfma_f32_16x16x32_bf16 v[48:51], v[188:191], v[196:199], v[48:51]
	v_mfma_f32_16x16x32_bf16 v[32:35], v[188:191], v[204:207], v[32:35]
	v_mfma_f32_16x16x32_bf16 v[32:35], v[192:195], v[208:211], v[32:35]
	v_mfma_f32_16x16x32_bf16 v[36:39], v[184:187], v[208:211], v[36:39]
	v_mfma_f32_16x16x32_bf16 v[36:39], v[180:183], v[204:207], v[36:39]
	v_mfma_f32_16x16x32_bf16 v[40:43], v[172:175], v[204:207], v[40:43]
	v_mfma_f32_16x16x32_bf16 v[40:43], v[176:179], v[208:211], v[40:43]
	v_mfma_f32_16x16x32_bf16 v[44:47], v[154:157], v[208:211], v[44:47]
	v_mfma_f32_16x16x32_bf16 v[44:47], v[128:131], v[204:207], v[44:47]
	v_mfma_f32_16x16x32_bf16 v[28:31], v[128:131], v[212:215], v[28:31]
	v_mfma_f32_16x16x32_bf16 v[28:31], v[154:157], v[216:219], v[28:31]
	v_mfma_f32_16x16x32_bf16 v[24:27], v[176:179], v[216:219], v[24:27]
	v_mfma_f32_16x16x32_bf16 v[24:27], v[172:175], v[212:215], v[24:27]
	v_mfma_f32_16x16x32_bf16 v[20:23], v[180:183], v[212:215], v[20:23]
	v_mfma_f32_16x16x32_bf16 v[20:23], v[184:187], v[216:219], v[20:23]
	v_mfma_f32_16x16x32_bf16 v[16:19], v[192:195], v[216:219], v[16:19]
	v_mfma_f32_16x16x32_bf16 v[16:19], v[188:191], v[212:215], v[16:19]
	v_mfma_f32_16x16x32_bf16 v[0:3], v[188:191], v[220:223], v[0:3]
	v_mfma_f32_16x16x32_bf16 v[0:3], v[192:195], v[224:227], v[0:3]
	v_mfma_f32_16x16x32_bf16 v[4:7], v[184:187], v[224:227], v[4:7]
	v_mfma_f32_16x16x32_bf16 v[4:7], v[180:183], v[220:223], v[4:7]
	v_mfma_f32_16x16x32_bf16 v[8:11], v[172:175], v[220:223], v[8:11]
	v_mfma_f32_16x16x32_bf16 v[8:11], v[176:179], v[224:227], v[8:11]
	v_mfma_f32_16x16x32_bf16 v[12:15], v[154:157], v[224:227], v[12:15]
	v_mfma_f32_16x16x32_bf16 v[12:15], v[128:131], v[220:223], v[12:15]
	s_barrier
	s_add_i32 s55, 0, 0x18000
	v_add_u32_e32 v153, s55, v159
	s_add_i32 s56, 0, 0x1c000
	ds_read_b128 v[128:131], v153
	ds_read_b128 v[154:157], v153 offset:1024
	ds_read_b128 v[172:175], v153 offset:2048
	ds_read_b128 v[176:179], v153 offset:3072
	v_add_u32_e32 v153, s56, v159
	ds_read_b128 v[180:183], v153
	ds_read_b128 v[184:187], v153 offset:1024
	ds_read_b128 v[188:191], v153 offset:2048
	ds_read_b128 v[192:195], v153 offset:3072
	s_add_u32 s20, s26, 0x100000
	s_addc_u32 s21, s27, 0
	s_mov_b32 m0, s37
	v_lshl_add_u64 v[196:197], s[20:21], 0, v[132:133]
	global_load_lds_dwordx4 v[196:197], off
	v_lshl_add_u64 v[196:197], s[20:21], 0, v[136:137]
	s_mov_b32 m0, s38
	s_nop 0
	global_load_lds_dwordx4 v[196:197], off
	ds_read_b128 v[196:199], v169 offset:32768
	ds_read_b128 v[200:203], v169 offset:33792
	ds_read_b128 v[204:207], v169 offset:34816
	ds_read_b128 v[208:211], v169 offset:35840
	ds_read_b128 v[212:215], v169 offset:36864
	ds_read_b128 v[216:219], v169 offset:37888
	ds_read_b128 v[220:223], v169 offset:38912
	ds_read_b128 v[224:227], v169 offset:39936
	s_waitcnt vmcnt(8)
	s_waitcnt lgkmcnt(0)
	s_barrier
	v_mfma_f32_16x16x32_bf16 v[124:127], v[128:131], v[196:199], v[124:127]
	v_mfma_f32_16x16x32_bf16 v[124:127], v[154:157], v[200:203], v[124:127]
	v_mfma_f32_16x16x32_bf16 v[120:123], v[176:179], v[200:203], v[120:123]
	v_mfma_f32_16x16x32_bf16 v[120:123], v[172:175], v[196:199], v[120:123]
	v_mfma_f32_16x16x32_bf16 v[116:119], v[180:183], v[196:199], v[116:119]
	v_mfma_f32_16x16x32_bf16 v[116:119], v[184:187], v[200:203], v[116:119]
	v_mfma_f32_16x16x32_bf16 v[112:115], v[192:195], v[200:203], v[112:115]
	v_mfma_f32_16x16x32_bf16 v[112:115], v[188:191], v[196:199], v[112:115]
	v_mfma_f32_16x16x32_bf16 v[96:99], v[188:191], v[204:207], v[96:99]
	v_mfma_f32_16x16x32_bf16 v[96:99], v[192:195], v[208:211], v[96:99]
	v_mfma_f32_16x16x32_bf16 v[100:103], v[184:187], v[208:211], v[100:103]
	v_mfma_f32_16x16x32_bf16 v[100:103], v[180:183], v[204:207], v[100:103]
	v_mfma_f32_16x16x32_bf16 v[104:107], v[172:175], v[204:207], v[104:107]
	v_mfma_f32_16x16x32_bf16 v[104:107], v[176:179], v[208:211], v[104:107]
	v_mfma_f32_16x16x32_bf16 v[108:111], v[154:157], v[208:211], v[108:111]
	v_mfma_f32_16x16x32_bf16 v[108:111], v[128:131], v[204:207], v[108:111]
	v_mfma_f32_16x16x32_bf16 v[92:95], v[128:131], v[212:215], v[92:95]
	v_mfma_f32_16x16x32_bf16 v[92:95], v[154:157], v[216:219], v[92:95]
	v_mfma_f32_16x16x32_bf16 v[88:91], v[176:179], v[216:219], v[88:91]
	v_mfma_f32_16x16x32_bf16 v[88:91], v[172:175], v[212:215], v[88:91]
	v_mfma_f32_16x16x32_bf16 v[84:87], v[180:183], v[212:215], v[84:87]
	v_mfma_f32_16x16x32_bf16 v[84:87], v[184:187], v[216:219], v[84:87]
	v_mfma_f32_16x16x32_bf16 v[80:83], v[192:195], v[216:219], v[80:83]
	v_mfma_f32_16x16x32_bf16 v[80:83], v[188:191], v[212:215], v[80:83]
	v_mfma_f32_16x16x32_bf16 v[64:67], v[188:191], v[220:223], v[64:67]
	v_mfma_f32_16x16x32_bf16 v[64:67], v[192:195], v[224:227], v[64:67]
	v_mfma_f32_16x16x32_bf16 v[68:71], v[184:187], v[224:227], v[68:71]
	v_mfma_f32_16x16x32_bf16 v[68:71], v[180:183], v[220:223], v[68:71]
	v_mfma_f32_16x16x32_bf16 v[72:75], v[172:175], v[220:223], v[72:75]
	v_mfma_f32_16x16x32_bf16 v[72:75], v[176:179], v[224:227], v[72:75]
	v_mfma_f32_16x16x32_bf16 v[76:79], v[154:157], v[224:227], v[76:79]
	v_mfma_f32_16x16x32_bf16 v[76:79], v[128:131], v[220:223], v[76:79]
	s_barrier
	s_add_i32 s20, s55, s30
	v_lshl_add_u64 v[160:161], v[160:161], 0, s[8:9]
	s_mov_b32 m0, s20
	s_nop 0
	global_load_lds_dwordx4 v[160:161], off
	s_add_i32 m0, s20, 0x2000
	s_add_u32 s20, s24, 0x100800
	v_lshl_add_u64 v[160:161], v[164:165], 0, s[8:9]
	s_addc_u32 s21, s25, 0
	s_add_i32 s24, s56, s30
	global_load_lds_dwordx4 v[160:161], off
	v_lshl_add_u64 v[160:161], s[20:21], 0, v[134:135]
	s_mov_b32 m0, s24
	s_nop 0
	global_load_lds_dwordx4 v[160:161], off
	v_lshl_add_u64 v[160:161], s[20:21], 0, v[138:139]
	s_add_i32 m0, s24, 0x2000
	s_nop 0
	global_load_lds_dwordx4 v[160:161], off
	v_lshl_add_u64 v[160:161], v[228:229], 0, s[8:9]
	s_mov_b32 m0, s41
	s_nop 0
	global_load_lds_dwordx4 v[160:161], off
	v_lshl_add_u64 v[160:161], v[230:231], 0, s[8:9]
	s_mov_b32 m0, s42
	s_nop 0
	global_load_lds_dwordx4 v[160:161], off
	ds_read_b128 v[196:199], v169 offset:49152
	ds_read_b128 v[200:203], v169 offset:50176
	ds_read_b128 v[204:207], v169 offset:51200
	ds_read_b128 v[208:211], v169 offset:52224
	ds_read_b128 v[212:215], v169 offset:53248
	ds_read_b128 v[216:219], v169 offset:54272
	ds_read_b128 v[220:223], v169 offset:55296
	ds_read_b128 v[224:227], v169 offset:56320
	s_waitcnt vmcnt(8)
	s_waitcnt lgkmcnt(0)
	s_barrier
	v_mfma_f32_16x16x32_bf16 v[60:63], v[128:131], v[196:199], v[60:63]
	v_mfma_f32_16x16x32_bf16 v[60:63], v[154:157], v[200:203], v[60:63]
	v_mfma_f32_16x16x32_bf16 v[56:59], v[176:179], v[200:203], v[56:59]
	v_mfma_f32_16x16x32_bf16 v[56:59], v[172:175], v[196:199], v[56:59]
	v_mfma_f32_16x16x32_bf16 v[52:55], v[180:183], v[196:199], v[52:55]
	v_mfma_f32_16x16x32_bf16 v[52:55], v[184:187], v[200:203], v[52:55]
	v_mfma_f32_16x16x32_bf16 v[48:51], v[192:195], v[200:203], v[48:51]
	v_mfma_f32_16x16x32_bf16 v[48:51], v[188:191], v[196:199], v[48:51]
	v_mfma_f32_16x16x32_bf16 v[32:35], v[188:191], v[204:207], v[32:35]
	v_mfma_f32_16x16x32_bf16 v[32:35], v[192:195], v[208:211], v[32:35]
	v_mfma_f32_16x16x32_bf16 v[36:39], v[184:187], v[208:211], v[36:39]
	v_mfma_f32_16x16x32_bf16 v[36:39], v[180:183], v[204:207], v[36:39]
	v_mfma_f32_16x16x32_bf16 v[40:43], v[172:175], v[204:207], v[40:43]
	v_mfma_f32_16x16x32_bf16 v[40:43], v[176:179], v[208:211], v[40:43]
	v_mfma_f32_16x16x32_bf16 v[44:47], v[154:157], v[208:211], v[44:47]
	v_mfma_f32_16x16x32_bf16 v[44:47], v[128:131], v[204:207], v[44:47]
	v_mfma_f32_16x16x32_bf16 v[28:31], v[128:131], v[212:215], v[28:31]
	v_mfma_f32_16x16x32_bf16 v[28:31], v[154:157], v[216:219], v[28:31]
	v_mfma_f32_16x16x32_bf16 v[24:27], v[176:179], v[216:219], v[24:27]
	v_mfma_f32_16x16x32_bf16 v[24:27], v[172:175], v[212:215], v[24:27]
	v_mfma_f32_16x16x32_bf16 v[20:23], v[180:183], v[212:215], v[20:23]
	v_mfma_f32_16x16x32_bf16 v[20:23], v[184:187], v[216:219], v[20:23]
	v_mfma_f32_16x16x32_bf16 v[16:19], v[192:195], v[216:219], v[16:19]
	v_mfma_f32_16x16x32_bf16 v[16:19], v[188:191], v[212:215], v[16:19]
	v_mfma_f32_16x16x32_bf16 v[0:3], v[188:191], v[220:223], v[0:3]
	v_mfma_f32_16x16x32_bf16 v[0:3], v[192:195], v[224:227], v[0:3]
	v_mfma_f32_16x16x32_bf16 v[4:7], v[184:187], v[224:227], v[4:7]
	v_mfma_f32_16x16x32_bf16 v[4:7], v[180:183], v[220:223], v[4:7]
	v_mfma_f32_16x16x32_bf16 v[8:11], v[172:175], v[220:223], v[8:11]
	v_mfma_f32_16x16x32_bf16 v[8:11], v[176:179], v[224:227], v[8:11]
	v_mfma_f32_16x16x32_bf16 v[12:15], v[154:157], v[224:227], v[12:15]
	v_mfma_f32_16x16x32_bf16 v[12:15], v[128:131], v[220:223], v[12:15]
	s_barrier
	s_add_i32 s54, s54, 2
	s_add_u32 s52, s52, 0x1000
	s_addc_u32 s53, s53, 0
	s_cmp_gt_u32 s54, 61
	s_mov_b64 s[20:21], s[22:23]
	s_cbranch_scc0 .LBB0_1543
	s_setprio 0

.LBB0_1624:
	s_sub_i32 s17, s52, 32
	s_ashr_i32 s18, s52, 31
	s_cmp_lt_i32 s52, 32
	s_cselect_b32 s19, s18, 0
	s_cselect_b32 s18, s52, s17
	s_cselect_b32 s17, s31, s34
	s_cselect_b32 s20, s30, s33
	s_lshl_b64 s[18:19], s[18:19], 23
	s_add_u32 s18, s20, s18
	s_addc_u32 s19, s17, s19
	s_and_b64 s[20:21], s[4:5], exec
	s_cselect_b32 s29, s19, s23
	s_cselect_b32 s53, s18, s22
	s_ashr_i32 s17, s16, 31
	s_lshl_b64 s[20:21], s[16:17], 23
	s_add_u32 s20, s35, s20
	s_addc_u32 s21, s36, s21
	s_and_b64 s[26:27], s[4:5], exec
	s_cselect_b32 s17, s21, s25
	s_cselect_b32 s54, s20, s24
	s_add_u32 s22, s22, 0x400800
	s_addc_u32 s23, s23, 0
	s_add_u32 s55, s24, 0x1000
	v_mov_b32_e32 v0, 0
	s_addc_u32 s56, s25, 0
	s_mov_b32 s57, -2
	s_waitcnt lgkmcnt(0)
	v_mov_b32_e32 v1, v0
	v_mov_b32_e32 v2, v0
	v_mov_b32_e32 v3, v0
	v_mov_b32_e32 v4, v0
	v_mov_b32_e32 v5, v0
	v_mov_b32_e32 v6, v0
	v_mov_b32_e32 v7, v0
	v_mov_b32_e32 v16, v0
	v_mov_b32_e32 v17, v0
	v_mov_b32_e32 v18, v0
	v_mov_b32_e32 v19, v0
	v_mov_b32_e32 v20, v0
	v_mov_b32_e32 v21, v0
	v_mov_b32_e32 v22, v0
	v_mov_b32_e32 v23, v0
	v_mov_b32_e32 v32, v0
	v_mov_b32_e32 v33, v0
	v_mov_b32_e32 v34, v0
	v_mov_b32_e32 v35, v0
	v_mov_b32_e32 v36, v0
	v_mov_b32_e32 v37, v0
	v_mov_b32_e32 v38, v0
	v_mov_b32_e32 v39, v0
	v_mov_b32_e32 v48, v0
	v_mov_b32_e32 v49, v0
	v_mov_b32_e32 v50, v0
	v_mov_b32_e32 v51, v0
	v_mov_b32_e32 v52, v0
	v_mov_b32_e32 v53, v0
	v_mov_b32_e32 v54, v0
	v_mov_b32_e32 v55, v0
	v_mov_b32_e32 v8, v0
	v_mov_b32_e32 v9, v0
	v_mov_b32_e32 v10, v0
	v_mov_b32_e32 v11, v0
	v_mov_b32_e32 v12, v0
	v_mov_b32_e32 v13, v0
	v_mov_b32_e32 v14, v0
	v_mov_b32_e32 v15, v0
	v_mov_b32_e32 v24, v0
	v_mov_b32_e32 v25, v0
	v_mov_b32_e32 v26, v0
	v_mov_b32_e32 v27, v0
	v_mov_b32_e32 v28, v0
	v_mov_b32_e32 v29, v0
	v_mov_b32_e32 v30, v0
	v_mov_b32_e32 v31, v0
	v_mov_b32_e32 v40, v0
	v_mov_b32_e32 v41, v0
	v_mov_b32_e32 v42, v0
	v_mov_b32_e32 v43, v0
	v_mov_b32_e32 v44, v0
	v_mov_b32_e32 v45, v0
	v_mov_b32_e32 v46, v0
	v_mov_b32_e32 v47, v0
	v_mov_b32_e32 v56, v0
	v_mov_b32_e32 v57, v0
	v_mov_b32_e32 v58, v0
	v_mov_b32_e32 v59, v0
	v_mov_b32_e32 v60, v0
	v_mov_b32_e32 v61, v0
	v_mov_b32_e32 v62, v0
	v_mov_b32_e32 v63, v0
	v_mov_b32_e32 v64, v0
	v_mov_b32_e32 v65, v0
	v_mov_b32_e32 v66, v0
	v_mov_b32_e32 v67, v0
	v_mov_b32_e32 v68, v0
	v_mov_b32_e32 v69, v0
	v_mov_b32_e32 v70, v0
	v_mov_b32_e32 v71, v0
	v_mov_b32_e32 v80, v0
	v_mov_b32_e32 v81, v0
	v_mov_b32_e32 v82, v0
	v_mov_b32_e32 v83, v0
	v_mov_b32_e32 v84, v0
	v_mov_b32_e32 v85, v0
	v_mov_b32_e32 v86, v0
	v_mov_b32_e32 v87, v0
	v_mov_b32_e32 v96, v0
	v_mov_b32_e32 v97, v0
	v_mov_b32_e32 v98, v0
	v_mov_b32_e32 v99, v0
	v_mov_b32_e32 v100, v0
	v_mov_b32_e32 v101, v0
	v_mov_b32_e32 v102, v0
	v_mov_b32_e32 v103, v0
	v_mov_b32_e32 v112, v0
	v_mov_b32_e32 v113, v0
	v_mov_b32_e32 v114, v0
	v_mov_b32_e32 v115, v0
	v_mov_b32_e32 v116, v0
	v_mov_b32_e32 v117, v0
	v_mov_b32_e32 v118, v0
	v_mov_b32_e32 v119, v0
	v_mov_b32_e32 v72, v0
	v_mov_b32_e32 v73, v0
	v_mov_b32_e32 v74, v0
	v_mov_b32_e32 v75, v0
	v_mov_b32_e32 v76, v0
	v_mov_b32_e32 v77, v0
	v_mov_b32_e32 v78, v0
	v_mov_b32_e32 v79, v0
	v_mov_b32_e32 v88, v0
	v_mov_b32_e32 v89, v0
	v_mov_b32_e32 v90, v0
	v_mov_b32_e32 v91, v0
	v_mov_b32_e32 v92, v0
	v_mov_b32_e32 v93, v0
	v_mov_b32_e32 v94, v0
	v_mov_b32_e32 v95, v0
	v_mov_b32_e32 v104, v0
	v_mov_b32_e32 v105, v0
	v_mov_b32_e32 v106, v0
	v_mov_b32_e32 v107, v0
	v_mov_b32_e32 v108, v0
	v_mov_b32_e32 v109, v0
	v_mov_b32_e32 v110, v0
	v_mov_b32_e32 v111, v0
	v_mov_b32_e32 v120, v0
	v_mov_b32_e32 v121, v0
	v_mov_b32_e32 v122, v0
	v_mov_b32_e32 v123, v0
	v_mov_b32_e32 v124, v0
	v_mov_b32_e32 v125, v0
	v_mov_b32_e32 v126, v0
	v_mov_b32_e32 v127, v0
	s_and_b64 vcc, exec, s[6:7]
	s_cbranch_vccnz .Lsprio_P9
	s_setprio 1

.LBB0_1625:
	ds_read_b128 v[128:131], v177
	ds_read_b128 v[132:135], v177 offset:1024
	ds_read_b128 v[136:139], v177 offset:2048
	ds_read_b128 v[140:143], v177 offset:3072
	ds_read_b128 v[144:147], v178
	ds_read_b128 v[148:151], v178 offset:1024
	ds_read_b128 v[170:173], v178 offset:2048
	ds_read_b128 v[182:185], v178 offset:3072
	s_add_u32 s24, s22, 0xffc00800
	s_addc_u32 s25, s23, -1
	s_cmpk_eq_i32 s57, 0xfc
	s_cselect_b32 s27, s29, s25
	s_cselect_b32 s26, s53, s24
	s_cselect_b32 s25, s17, s56
	s_cselect_b32 s24, s54, s55
	v_lshl_add_u64 v[186:187], s[22:23], 0, v[162:163]
	s_add_i32 m0, s38, 0xc000
	s_nop 0
	global_load_lds_dwordx4 v[186:187], off
	v_lshl_add_u64 v[186:187], s[22:23], 0, v[164:165]
	s_add_i32 m0, s38, 0xe000
	s_nop 0
	global_load_lds_dwordx4 v[186:187], off
	ds_read_b128 v[186:189], v179
	ds_read_b128 v[190:193], v179 offset:1024
	ds_read_b128 v[194:197], v179 offset:2048
	ds_read_b128 v[198:201], v179 offset:3072
	ds_read_b128 v[202:205], v179 offset:4096
	ds_read_b128 v[206:209], v179 offset:5120
	ds_read_b128 v[210:213], v179 offset:6144
	ds_read_b128 v[214:217], v179 offset:7168
	s_waitcnt vmcnt(8)
	s_waitcnt lgkmcnt(0)
	s_barrier
	v_mfma_f32_16x16x32_bf16 v[124:127], v[128:131], v[186:189], v[124:127]
	v_mfma_f32_16x16x32_bf16 v[124:127], v[132:135], v[190:193], v[124:127]
	v_mfma_f32_16x16x32_bf16 v[120:123], v[140:143], v[190:193], v[120:123]
	v_mfma_f32_16x16x32_bf16 v[120:123], v[136:139], v[186:189], v[120:123]
	v_mfma_f32_16x16x32_bf16 v[116:119], v[144:147], v[186:189], v[116:119]
	v_mfma_f32_16x16x32_bf16 v[116:119], v[148:151], v[190:193], v[116:119]
	v_mfma_f32_16x16x32_bf16 v[112:115], v[182:185], v[190:193], v[112:115]
	v_mfma_f32_16x16x32_bf16 v[112:115], v[170:173], v[186:189], v[112:115]
	v_mfma_f32_16x16x32_bf16 v[96:99], v[170:173], v[194:197], v[96:99]
	v_mfma_f32_16x16x32_bf16 v[96:99], v[182:185], v[198:201], v[96:99]
	v_mfma_f32_16x16x32_bf16 v[100:103], v[148:151], v[198:201], v[100:103]
	v_mfma_f32_16x16x32_bf16 v[100:103], v[144:147], v[194:197], v[100:103]
	v_mfma_f32_16x16x32_bf16 v[104:107], v[136:139], v[194:197], v[104:107]
	v_mfma_f32_16x16x32_bf16 v[104:107], v[140:143], v[198:201], v[104:107]
	v_mfma_f32_16x16x32_bf16 v[108:111], v[132:135], v[198:201], v[108:111]
	v_mfma_f32_16x16x32_bf16 v[108:111], v[128:131], v[194:197], v[108:111]
	v_mfma_f32_16x16x32_bf16 v[92:95], v[128:131], v[202:205], v[92:95]
	v_mfma_f32_16x16x32_bf16 v[92:95], v[132:135], v[206:209], v[92:95]
	v_mfma_f32_16x16x32_bf16 v[88:91], v[140:143], v[206:209], v[88:91]
	v_mfma_f32_16x16x32_bf16 v[88:91], v[136:139], v[202:205], v[88:91]
	v_mfma_f32_16x16x32_bf16 v[84:87], v[144:147], v[202:205], v[84:87]
	v_mfma_f32_16x16x32_bf16 v[84:87], v[148:151], v[206:209], v[84:87]
	v_mfma_f32_16x16x32_bf16 v[80:83], v[182:185], v[206:209], v[80:83]
	v_mfma_f32_16x16x32_bf16 v[80:83], v[170:173], v[202:205], v[80:83]
	v_mfma_f32_16x16x32_bf16 v[64:67], v[170:173], v[210:213], v[64:67]
	v_mfma_f32_16x16x32_bf16 v[64:67], v[182:185], v[214:217], v[64:67]
	v_mfma_f32_16x16x32_bf16 v[68:71], v[148:151], v[214:217], v[68:71]
	v_mfma_f32_16x16x32_bf16 v[68:71], v[144:147], v[210:213], v[68:71]
	v_mfma_f32_16x16x32_bf16 v[72:75], v[136:139], v[210:213], v[72:75]
	v_mfma_f32_16x16x32_bf16 v[72:75], v[140:143], v[214:217], v[72:75]
	v_mfma_f32_16x16x32_bf16 v[76:79], v[132:135], v[214:217], v[76:79]
	v_mfma_f32_16x16x32_bf16 v[76:79], v[128:131], v[210:213], v[76:79]
	s_barrier
	s_add_i32 s58, s48, s37
	v_lshl_add_u64 v[218:219], s[24:25], 0, v[154:155]
	s_mov_b32 m0, s58
	v_lshl_add_u64 v[220:221], s[24:25], 0, v[158:159]
	global_load_lds_dwordx4 v[218:219], off
	s_add_i32 m0, s58, 0x2000
	s_add_u32 s58, s24, 0x400000
	s_addc_u32 s59, s25, 0
	s_add_i32 s60, s49, s37
	global_load_lds_dwordx4 v[220:221], off
	v_lshl_add_u64 v[186:187], s[58:59], 0, v[154:155]
	s_mov_b32 m0, s60
	v_lshl_add_u64 v[222:223], s[26:27], 0, v[152:153]
	global_load_lds_dwordx4 v[186:187], off
	v_lshl_add_u64 v[186:187], s[58:59], 0, v[158:159]
	s_add_i32 m0, s60, 0x2000
	v_lshl_add_u64 v[224:225], s[26:27], 0, v[156:157]
	global_load_lds_dwordx4 v[186:187], off
	s_mov_b32 m0, s38
	s_nop 0
	global_load_lds_dwordx4 v[222:223], off
	s_mov_b32 m0, s39
	s_nop 0
	global_load_lds_dwordx4 v[224:225], off
	ds_read_b128 v[186:189], v179 offset:16384
	ds_read_b128 v[190:193], v179 offset:17408
	ds_read_b128 v[194:197], v179 offset:18432
	ds_read_b128 v[198:201], v179 offset:19456
	ds_read_b128 v[202:205], v179 offset:20480
	ds_read_b128 v[206:209], v179 offset:21504
	ds_read_b128 v[210:213], v179 offset:22528
	ds_read_b128 v[214:217], v179 offset:23552
	s_waitcnt vmcnt(8)
	s_waitcnt lgkmcnt(0)
	s_barrier
	v_mfma_f32_16x16x32_bf16 v[60:63], v[128:131], v[186:189], v[60:63]
	v_mfma_f32_16x16x32_bf16 v[60:63], v[132:135], v[190:193], v[60:63]
	v_mfma_f32_16x16x32_bf16 v[56:59], v[140:143], v[190:193], v[56:59]
	v_mfma_f32_16x16x32_bf16 v[56:59], v[136:139], v[186:189], v[56:59]
	v_mfma_f32_16x16x32_bf16 v[52:55], v[144:147], v[186:189], v[52:55]
	v_mfma_f32_16x16x32_bf16 v[52:55], v[148:151], v[190:193], v[52:55]
	v_mfma_f32_16x16x32_bf16 v[48:51], v[182:185], v[190:193], v[48:51]
	v_mfma_f32_16x16x32_bf16 v[48:51], v[170:173], v[186:189], v[48:51]
	v_mfma_f32_16x16x32_bf16 v[32:35], v[170:173], v[194:197], v[32:35]
	v_mfma_f32_16x16x32_bf16 v[32:35], v[182:185], v[198:201], v[32:35]
	v_mfma_f32_16x16x32_bf16 v[36:39], v[148:151], v[198:201], v[36:39]
	v_mfma_f32_16x16x32_bf16 v[36:39], v[144:147], v[194:197], v[36:39]
	v_mfma_f32_16x16x32_bf16 v[40:43], v[136:139], v[194:197], v[40:43]
	v_mfma_f32_16x16x32_bf16 v[40:43], v[140:143], v[198:201], v[40:43]
	v_mfma_f32_16x16x32_bf16 v[44:47], v[132:135], v[198:201], v[44:47]
	v_mfma_f32_16x16x32_bf16 v[44:47], v[128:131], v[194:197], v[44:47]
	v_mfma_f32_16x16x32_bf16 v[28:31], v[128:131], v[202:205], v[28:31]
	v_mfma_f32_16x16x32_bf16 v[28:31], v[132:135], v[206:209], v[28:31]
	v_mfma_f32_16x16x32_bf16 v[24:27], v[140:143], v[206:209], v[24:27]
	v_mfma_f32_16x16x32_bf16 v[24:27], v[136:139], v[202:205], v[24:27]
	v_mfma_f32_16x16x32_bf16 v[20:23], v[144:147], v[202:205], v[20:23]
	v_mfma_f32_16x16x32_bf16 v[20:23], v[148:151], v[206:209], v[20:23]
	v_mfma_f32_16x16x32_bf16 v[16:19], v[182:185], v[206:209], v[16:19]
	v_mfma_f32_16x16x32_bf16 v[16:19], v[170:173], v[202:205], v[16:19]
	v_mfma_f32_16x16x32_bf16 v[0:3], v[170:173], v[210:213], v[0:3]
	v_mfma_f32_16x16x32_bf16 v[0:3], v[182:185], v[214:217], v[0:3]
	v_mfma_f32_16x16x32_bf16 v[4:7], v[148:151], v[214:217], v[4:7]
	v_mfma_f32_16x16x32_bf16 v[4:7], v[144:147], v[210:213], v[4:7]
	v_mfma_f32_16x16x32_bf16 v[8:11], v[136:139], v[210:213], v[8:11]
	v_mfma_f32_16x16x32_bf16 v[8:11], v[140:143], v[214:217], v[8:11]
	v_mfma_f32_16x16x32_bf16 v[12:15], v[132:135], v[214:217], v[12:15]
	v_mfma_f32_16x16x32_bf16 v[12:15], v[128:131], v[210:213], v[12:15]
	s_barrier
	s_add_i32 s58, 0, 0x18000
	s_add_i32 s59, 0, 0x1c000
	v_add_u32_e32 v140, s58, v174
	v_add_u32_e32 v181, s59, v174
	ds_read_b128 v[128:131], v140
	ds_read_b128 v[132:135], v140 offset:1024
	ds_read_b128 v[136:139], v140 offset:2048
	ds_read_b128 v[140:143], v140 offset:3072
	ds_read_b128 v[144:147], v181
	ds_read_b128 v[148:151], v181 offset:1024
	ds_read_b128 v[170:173], v181 offset:2048
	ds_read_b128 v[182:185], v181 offset:3072
	s_add_u32 s26, s26, 0x400000
	s_addc_u32 s27, s27, 0
	s_mov_b32 m0, s40
	v_lshl_add_u64 v[186:187], s[26:27], 0, v[152:153]
	global_load_lds_dwordx4 v[186:187], off
	v_lshl_add_u64 v[186:187], s[26:27], 0, v[156:157]
	s_mov_b32 m0, s41
	s_nop 0
	global_load_lds_dwordx4 v[186:187], off
	ds_read_b128 v[186:189], v179 offset:32768
	ds_read_b128 v[190:193], v179 offset:33792
	ds_read_b128 v[194:197], v179 offset:34816
	ds_read_b128 v[198:201], v179 offset:35840
	ds_read_b128 v[202:205], v179 offset:36864
	ds_read_b128 v[206:209], v179 offset:37888
	ds_read_b128 v[210:213], v179 offset:38912
	ds_read_b128 v[214:217], v179 offset:39936
	s_waitcnt vmcnt(8)
	s_waitcnt lgkmcnt(0)
	s_barrier
	v_mfma_f32_16x16x32_bf16 v[124:127], v[128:131], v[186:189], v[124:127]
	v_mfma_f32_16x16x32_bf16 v[124:127], v[132:135], v[190:193], v[124:127]
	v_mfma_f32_16x16x32_bf16 v[120:123], v[140:143], v[190:193], v[120:123]
	v_mfma_f32_16x16x32_bf16 v[120:123], v[136:139], v[186:189], v[120:123]
	v_mfma_f32_16x16x32_bf16 v[116:119], v[144:147], v[186:189], v[116:119]
	v_mfma_f32_16x16x32_bf16 v[116:119], v[148:151], v[190:193], v[116:119]
	v_mfma_f32_16x16x32_bf16 v[112:115], v[182:185], v[190:193], v[112:115]
	v_mfma_f32_16x16x32_bf16 v[112:115], v[170:173], v[186:189], v[112:115]
	v_mfma_f32_16x16x32_bf16 v[96:99], v[170:173], v[194:197], v[96:99]
	v_mfma_f32_16x16x32_bf16 v[96:99], v[182:185], v[198:201], v[96:99]
	v_mfma_f32_16x16x32_bf16 v[100:103], v[148:151], v[198:201], v[100:103]
	v_mfma_f32_16x16x32_bf16 v[100:103], v[144:147], v[194:197], v[100:103]
	v_mfma_f32_16x16x32_bf16 v[104:107], v[136:139], v[194:197], v[104:107]
	v_mfma_f32_16x16x32_bf16 v[104:107], v[140:143], v[198:201], v[104:107]
	v_mfma_f32_16x16x32_bf16 v[108:111], v[132:135], v[198:201], v[108:111]
	v_mfma_f32_16x16x32_bf16 v[108:111], v[128:131], v[194:197], v[108:111]
	v_mfma_f32_16x16x32_bf16 v[92:95], v[128:131], v[202:205], v[92:95]
	v_mfma_f32_16x16x32_bf16 v[92:95], v[132:135], v[206:209], v[92:95]
	v_mfma_f32_16x16x32_bf16 v[88:91], v[140:143], v[206:209], v[88:91]
	v_mfma_f32_16x16x32_bf16 v[88:91], v[136:139], v[202:205], v[88:91]
	v_mfma_f32_16x16x32_bf16 v[84:87], v[144:147], v[202:205], v[84:87]
	v_mfma_f32_16x16x32_bf16 v[84:87], v[148:151], v[206:209], v[84:87]
	v_mfma_f32_16x16x32_bf16 v[80:83], v[182:185], v[206:209], v[80:83]
	v_mfma_f32_16x16x32_bf16 v[80:83], v[170:173], v[202:205], v[80:83]
	v_mfma_f32_16x16x32_bf16 v[64:67], v[170:173], v[210:213], v[64:67]
	v_mfma_f32_16x16x32_bf16 v[64:67], v[182:185], v[214:217], v[64:67]
	v_mfma_f32_16x16x32_bf16 v[68:71], v[148:151], v[214:217], v[68:71]
	v_mfma_f32_16x16x32_bf16 v[68:71], v[144:147], v[210:213], v[68:71]
	v_mfma_f32_16x16x32_bf16 v[72:75], v[136:139], v[210:213], v[72:75]
	v_mfma_f32_16x16x32_bf16 v[72:75], v[140:143], v[214:217], v[72:75]
	v_mfma_f32_16x16x32_bf16 v[76:79], v[132:135], v[214:217], v[76:79]
	v_mfma_f32_16x16x32_bf16 v[76:79], v[128:131], v[210:213], v[76:79]
	s_barrier
	s_add_i32 s26, s58, s37
	v_lshl_add_u64 v[186:187], v[218:219], 0, s[14:15]
	s_mov_b32 m0, s26
	s_nop 0
	global_load_lds_dwordx4 v[186:187], off
	s_add_i32 m0, s26, 0x2000
	s_add_u32 s24, s24, 0x400800
	v_lshl_add_u64 v[186:187], v[220:221], 0, s[14:15]
	s_addc_u32 s25, s25, 0
	s_add_i32 s26, s59, s37
	global_load_lds_dwordx4 v[186:187], off
	v_lshl_add_u64 v[186:187], s[24:25], 0, v[154:155]
	s_mov_b32 m0, s26
	s_nop 0
	global_load_lds_dwordx4 v[186:187], off
	v_lshl_add_u64 v[186:187], s[24:25], 0, v[158:159]
	s_add_i32 m0, s26, 0x2000
	s_nop 0
	global_load_lds_dwordx4 v[186:187], off
	v_lshl_add_u64 v[186:187], v[222:223], 0, s[14:15]
	s_mov_b32 m0, s43
	s_nop 0
	global_load_lds_dwordx4 v[186:187], off
	v_lshl_add_u64 v[186:187], v[224:225], 0, s[14:15]
	s_mov_b32 m0, s44
	s_nop 0
	global_load_lds_dwordx4 v[186:187], off
	ds_read_b128 v[186:189], v179 offset:49152
	ds_read_b128 v[190:193], v179 offset:50176
	ds_read_b128 v[194:197], v179 offset:51200
	ds_read_b128 v[198:201], v179 offset:52224
	ds_read_b128 v[202:205], v179 offset:53248
	ds_read_b128 v[206:209], v179 offset:54272
	ds_read_b128 v[210:213], v179 offset:55296
	ds_read_b128 v[214:217], v179 offset:56320
	s_waitcnt vmcnt(8)
	s_waitcnt lgkmcnt(0)
	s_barrier
	v_mfma_f32_16x16x32_bf16 v[60:63], v[128:131], v[186:189], v[60:63]
	v_mfma_f32_16x16x32_bf16 v[60:63], v[132:135], v[190:193], v[60:63]
	v_mfma_f32_16x16x32_bf16 v[56:59], v[140:143], v[190:193], v[56:59]
	v_mfma_f32_16x16x32_bf16 v[56:59], v[136:139], v[186:189], v[56:59]
	v_mfma_f32_16x16x32_bf16 v[52:55], v[144:147], v[186:189], v[52:55]
	v_mfma_f32_16x16x32_bf16 v[52:55], v[148:151], v[190:193], v[52:55]
	v_mfma_f32_16x16x32_bf16 v[48:51], v[182:185], v[190:193], v[48:51]
	v_mfma_f32_16x16x32_bf16 v[48:51], v[170:173], v[186:189], v[48:51]
	v_mfma_f32_16x16x32_bf16 v[32:35], v[170:173], v[194:197], v[32:35]
	v_mfma_f32_16x16x32_bf16 v[32:35], v[182:185], v[198:201], v[32:35]
	v_mfma_f32_16x16x32_bf16 v[36:39], v[148:151], v[198:201], v[36:39]
	v_mfma_f32_16x16x32_bf16 v[36:39], v[144:147], v[194:197], v[36:39]
	v_mfma_f32_16x16x32_bf16 v[40:43], v[136:139], v[194:197], v[40:43]
	v_mfma_f32_16x16x32_bf16 v[40:43], v[140:143], v[198:201], v[40:43]
	v_mfma_f32_16x16x32_bf16 v[44:47], v[132:135], v[198:201], v[44:47]
	v_mfma_f32_16x16x32_bf16 v[44:47], v[128:131], v[194:197], v[44:47]
	v_mfma_f32_16x16x32_bf16 v[28:31], v[128:131], v[202:205], v[28:31]
	v_mfma_f32_16x16x32_bf16 v[28:31], v[132:135], v[206:209], v[28:31]
	v_mfma_f32_16x16x32_bf16 v[24:27], v[140:143], v[206:209], v[24:27]
	v_mfma_f32_16x16x32_bf16 v[24:27], v[136:139], v[202:205], v[24:27]
	v_mfma_f32_16x16x32_bf16 v[20:23], v[144:147], v[202:205], v[20:23]
	v_mfma_f32_16x16x32_bf16 v[20:23], v[148:151], v[206:209], v[20:23]
	v_mfma_f32_16x16x32_bf16 v[16:19], v[182:185], v[206:209], v[16:19]
	v_mfma_f32_16x16x32_bf16 v[16:19], v[170:173], v[202:205], v[16:19]
	v_mfma_f32_16x16x32_bf16 v[0:3], v[170:173], v[210:213], v[0:3]
	v_mfma_f32_16x16x32_bf16 v[0:3], v[182:185], v[214:217], v[0:3]
	v_mfma_f32_16x16x32_bf16 v[4:7], v[148:151], v[214:217], v[4:7]
	v_mfma_f32_16x16x32_bf16 v[4:7], v[144:147], v[210:213], v[4:7]
	v_mfma_f32_16x16x32_bf16 v[8:11], v[136:139], v[210:213], v[8:11]
	v_mfma_f32_16x16x32_bf16 v[8:11], v[140:143], v[214:217], v[8:11]
	v_mfma_f32_16x16x32_bf16 v[12:15], v[132:135], v[214:217], v[12:15]
	v_mfma_f32_16x16x32_bf16 v[12:15], v[128:131], v[210:213], v[12:15]
	s_barrier
	s_add_i32 s57, s57, 2
	s_add_u32 s22, s22, 0x1000
	s_addc_u32 s23, s23, 0
	s_add_u32 s55, s55, 0x1000
	s_addc_u32 s56, s56, 0
	s_cmpk_gt_u32 s57, 0xfd
	s_cbranch_scc0 .LBB0_1625
	s_setprio 0
